# opt9 + GEMM main loops (7 of 8): LDS-DMA addresses in SGPR-base + 32-bit VGPR offset form, all 16 v_lshl_add_u64 per iteration removed
# speedup vs baseline: 1.0140x; 1.0140x over previous
; #define PG8_STAGE(bufoff, gbase, voff) do { _Pragma("unroll") for (int _i = 0; _i < 2; ++_i) \
;         __builtin_amdgcn_global_load_lds((const unsigned*)((const char*)(gbase) + (voff)[_i]), (LAS unsigned*)(lds + (bufoff) + ldsw + _i * 8192), 16, 0, 0); } while (0)
; #define PG8_LDA(dst, b, h) do { _Pragma("unroll") for (int m = 0; m < 4; ++m) _Pragma("unroll") for (int k = 0; k < 2; ++k) dst[m][k] = *(const LAS bf16x8*)(lds + PG8_SA(b, h) + aoff + m * 2048 + k * 1024); } while (0)
; #define PG8_LDB(dst, b, h) do { _Pragma("unroll") for (int n = 0; n < 2; ++n) _Pragma("unroll") for (int k = 0; k < 2; ++k) dst[n][k] = *(const LAS bf16x8*)(lds + PG8_SB(b, h) + boff + n * 2048 + k * 1024); } while (0)
; #define PG8_MMA(ai, bj, At, Bt) do { __builtin_amdgcn_s_setprio(1); _Pragma("unroll") for (int m = 0; m < 4; ++m) _Pragma("unroll") for (int n = 0; n < 2; ++n) _Pragma("unroll") for (int k = 0; k < 2; ++k) \
;         acc[ai][bj][m][n] = __builtin_amdgcn_mfma_f32_16x16x32_bf16(Bt[n][k], At[m][k], acc[ai][bj][m][n], 0, 0, 0); __builtin_amdgcn_s_setprio(0); } while (0)
; #define PG8_WAIT_V(n) asm volatile("s_waitcnt vmcnt(" #n ")" ::: "memory")
; template <class Epi>
; __device__ __forceinline__ void gemm_phase(LAS unsigned char* lds, const Gemm g, const StaticOrder& S, const Epi& E) {
;     ...
;         for (int t = 0; t < nt; t += 2) {
;             const bool last = (t == nt - 2);
;             if constexpr (Epi::HAS_MID) { if (t == nt1) E.mid(acc, cur, wr, wc, fr, fq); }
;             const char* a1 = cA + ((Epi::HAS_MID && t >= nt1) ? dA2 : 0) + (size_t)(t + 1) * kstep;
;             const char* a2 = last ? nA : cA + ((Epi::HAS_MID && t + 2 >= nt1) ? dA2 : 0) + (size_t)(t + 2) * kstep; const char* b2 = last ? nB : cB + ((Epi::HAS_MID && t + 2 >= nt1) ? dB2 : 0) + (size_t)(t + 2) * kstep;
;             const char* a3 = a2 + kstep; const char* b3 = b2 + kstep;
;             PG8_LDB(B0, 0, 0); PG8_LDB(B1, 0, 1); PG8_SCHED; PG8_LDA(At, 0, 0); PG8_STAGE(PG8_SA(1, 1), a1 + hsA, voffA);
;             PG8_WAIT_V(8); PG8_WAIT_L(0); PG8_BAR; PG8_MMA(0, 0, At, B0); PG8_MMA(0, 1, At, B1); PG8_BAR; PG8_SCHED;
;             PG8_LDA(At, 0, 1); PG8_STAGE(PG8_SB(0, 0), b2, voffB); PG8_STAGE(PG8_SB(0, 1), b2 + hsB, voffB); PG8_STAGE(PG8_SA(0, 0), a2, voffA);
;             PG8_WAIT_V(8); PG8_WAIT_L(0); PG8_BAR; PG8_MMA(1, 0, At, B0); PG8_MMA(1, 1, At, B1); PG8_BAR; PG8_SCHED;
.LBB0_214:
	ds_read_b128 v[144:147], v155
	ds_read_b128 v[148:151], v155 offset:1024
	ds_read_b128 v[162:165], v155 offset:2048
	ds_read_b128 v[166:169], v155 offset:3072
	ds_read_b128 v[180:183], v156
	ds_read_b128 v[184:187], v156 offset:1024
	ds_read_b128 v[188:191], v156 offset:2048
	ds_read_b128 v[192:195], v156 offset:3072
	s_add_u32 s38, s58, 0xfffc0080
	s_addc_u32 s39, s59, -1
	s_cmp_eq_u32 s37, 12
	s_cselect_b32 s63, s6, s39
	s_cselect_b32 s62, s7, s38
	s_cselect_b32 s61, s11, s36
	s_cselect_b32 s60, s13, s35
	s_add_i32 m0, s19, 0xc000
	ds_read_b128 v[196:199], v157
	ds_read_b128 v[200:203], v157 offset:1024
	ds_read_b128 v[204:207], v157 offset:2048
	ds_read_b128 v[208:211], v157 offset:3072
	ds_read_b128 v[212:215], v157 offset:4096
	ds_read_b128 v[216:219], v157 offset:5120
	ds_read_b128 v[220:223], v157 offset:6144
	ds_read_b128 v[224:227], v157 offset:7168
	global_load_lds_dwordx4 v136, s[58:59]
	s_add_i32 m0, s19, 0xe000
	s_nop 0
	global_load_lds_dwordx4 v138, s[58:59]
	s_waitcnt vmcnt(8)
	s_waitcnt lgkmcnt(0)
	s_barrier
	s_setprio 1
	s_waitcnt lgkmcnt(0)
	v_mfma_f32_16x16x32_bf16 v[124:127], v[144:147], v[196:199], v[124:127]
	v_mfma_f32_16x16x32_bf16 v[120:123], v[162:165], v[196:199], v[120:123]
	v_mfma_f32_16x16x32_bf16 v[108:111], v[144:147], v[204:207], v[108:111]
	v_mfma_f32_16x16x32_bf16 v[104:107], v[162:165], v[204:207], v[104:107]
	v_mfma_f32_16x16x32_bf16 v[92:95], v[144:147], v[212:215], v[92:95]
	v_mfma_f32_16x16x32_bf16 v[88:91], v[162:165], v[212:215], v[88:91]
	v_mfma_f32_16x16x32_bf16 v[76:79], v[144:147], v[220:223], v[76:79]
	v_mfma_f32_16x16x32_bf16 v[72:75], v[162:165], v[220:223], v[72:75]
	v_mfma_f32_16x16x32_bf16 v[124:127], v[148:151], v[200:203], v[124:127]
	v_mfma_f32_16x16x32_bf16 v[120:123], v[166:169], v[200:203], v[120:123]
	v_mfma_f32_16x16x32_bf16 v[108:111], v[148:151], v[208:211], v[108:111]
	v_mfma_f32_16x16x32_bf16 v[104:107], v[166:169], v[208:211], v[104:107]
	v_mfma_f32_16x16x32_bf16 v[92:95], v[148:151], v[216:219], v[92:95]
	v_mfma_f32_16x16x32_bf16 v[88:91], v[166:169], v[216:219], v[88:91]
	v_mfma_f32_16x16x32_bf16 v[76:79], v[148:151], v[224:227], v[76:79]
	v_mfma_f32_16x16x32_bf16 v[72:75], v[166:169], v[224:227], v[72:75]
	s_setprio 0
	s_setprio 1
	v_mfma_f32_16x16x32_bf16 v[116:119], v[180:183], v[196:199], v[116:119]
	v_mfma_f32_16x16x32_bf16 v[112:115], v[188:191], v[196:199], v[112:115]
	v_mfma_f32_16x16x32_bf16 v[100:103], v[180:183], v[204:207], v[100:103]
	v_mfma_f32_16x16x32_bf16 v[96:99], v[188:191], v[204:207], v[96:99]
	v_mfma_f32_16x16x32_bf16 v[84:87], v[180:183], v[212:215], v[84:87]
	v_mfma_f32_16x16x32_bf16 v[80:83], v[188:191], v[212:215], v[80:83]
	v_mfma_f32_16x16x32_bf16 v[68:71], v[180:183], v[220:223], v[68:71]
	v_mfma_f32_16x16x32_bf16 v[64:67], v[188:191], v[220:223], v[64:67]
	v_mfma_f32_16x16x32_bf16 v[116:119], v[184:187], v[200:203], v[116:119]
	v_mfma_f32_16x16x32_bf16 v[112:115], v[192:195], v[200:203], v[112:115]
	v_mfma_f32_16x16x32_bf16 v[100:103], v[184:187], v[208:211], v[100:103]
	v_mfma_f32_16x16x32_bf16 v[96:99], v[192:195], v[208:211], v[96:99]
	v_mfma_f32_16x16x32_bf16 v[84:87], v[184:187], v[216:219], v[84:87]
	v_mfma_f32_16x16x32_bf16 v[80:83], v[192:195], v[216:219], v[80:83]
	v_mfma_f32_16x16x32_bf16 v[68:71], v[184:187], v[224:227], v[68:71]
	v_mfma_f32_16x16x32_bf16 v[64:67], v[192:195], v[224:227], v[64:67]
	s_setprio 0
	s_barrier
	s_add_i32 s38, s30, s16
	s_mov_b32 m0, s38
	ds_read_b128 v[196:199], v157 offset:16384
	ds_read_b128 v[200:203], v157 offset:17408
	ds_read_b128 v[204:207], v157 offset:18432
	ds_read_b128 v[208:211], v157 offset:19456
	ds_read_b128 v[212:215], v157 offset:20480
	ds_read_b128 v[216:219], v157 offset:21504
	ds_read_b128 v[220:223], v157 offset:22528
	ds_read_b128 v[224:227], v157 offset:23552
	global_load_lds_dwordx4 v132, s[60:61]
	s_add_i32 m0, s38, 0x2000
	s_add_u32 s38, s60, 0x40000
	s_addc_u32 s39, s61, 0
	s_add_i32 s40, s31, s16
	global_load_lds_dwordx4 v128, s[60:61]
	s_mov_b32 m0, s40
	s_nop 0
	global_load_lds_dwordx4 v132, s[38:39]
	s_add_i32 m0, s40, 0x2000
	s_nop 0
	global_load_lds_dwordx4 v128, s[38:39]
	s_mov_b32 m0, s19
	s_nop 0
	global_load_lds_dwordx4 v134, s[62:63]
	s_mov_b32 m0, s22
	s_nop 0
	global_load_lds_dwordx4 v130, s[62:63]
	s_waitcnt vmcnt(8)
	s_waitcnt lgkmcnt(0)
	s_barrier
	s_setprio 1
	s_waitcnt lgkmcnt(0)
	v_mfma_f32_16x16x32_bf16 v[60:63], v[144:147], v[196:199], v[60:63]
	v_mfma_f32_16x16x32_bf16 v[56:59], v[162:165], v[196:199], v[56:59]
	v_mfma_f32_16x16x32_bf16 v[44:47], v[144:147], v[204:207], v[44:47]
	v_mfma_f32_16x16x32_bf16 v[40:43], v[162:165], v[204:207], v[40:43]
	v_mfma_f32_16x16x32_bf16 v[28:31], v[144:147], v[212:215], v[28:31]
	v_mfma_f32_16x16x32_bf16 v[24:27], v[162:165], v[212:215], v[24:27]
	v_mfma_f32_16x16x32_bf16 v[12:15], v[144:147], v[220:223], v[12:15]
	v_mfma_f32_16x16x32_bf16 v[8:11], v[162:165], v[220:223], v[8:11]
	v_mfma_f32_16x16x32_bf16 v[60:63], v[148:151], v[200:203], v[60:63]
	v_mfma_f32_16x16x32_bf16 v[56:59], v[166:169], v[200:203], v[56:59]
	v_mfma_f32_16x16x32_bf16 v[44:47], v[148:151], v[208:211], v[44:47]
	v_mfma_f32_16x16x32_bf16 v[40:43], v[166:169], v[208:211], v[40:43]
	v_mfma_f32_16x16x32_bf16 v[28:31], v[148:151], v[216:219], v[28:31]
	v_mfma_f32_16x16x32_bf16 v[24:27], v[166:169], v[216:219], v[24:27]
	v_mfma_f32_16x16x32_bf16 v[12:15], v[148:151], v[224:227], v[12:15]
	v_mfma_f32_16x16x32_bf16 v[8:11], v[166:169], v[224:227], v[8:11]
	s_setprio 0
	s_setprio 1
	v_mfma_f32_16x16x32_bf16 v[52:55], v[180:183], v[196:199], v[52:55]
	v_mfma_f32_16x16x32_bf16 v[48:51], v[188:191], v[196:199], v[48:51]
	v_mfma_f32_16x16x32_bf16 v[36:39], v[180:183], v[204:207], v[36:39]
	v_mfma_f32_16x16x32_bf16 v[32:35], v[188:191], v[204:207], v[32:35]
	v_mfma_f32_16x16x32_bf16 v[20:23], v[180:183], v[212:215], v[20:23]
	v_mfma_f32_16x16x32_bf16 v[16:19], v[188:191], v[212:215], v[16:19]
	v_mfma_f32_16x16x32_bf16 v[4:7], v[180:183], v[220:223], v[4:7]
	v_mfma_f32_16x16x32_bf16 v[0:3], v[188:191], v[220:223], v[0:3]
	v_mfma_f32_16x16x32_bf16 v[52:55], v[184:187], v[200:203], v[52:55]
	v_mfma_f32_16x16x32_bf16 v[48:51], v[192:195], v[200:203], v[48:51]
	v_mfma_f32_16x16x32_bf16 v[36:39], v[184:187], v[208:211], v[36:39]
	v_mfma_f32_16x16x32_bf16 v[32:35], v[192:195], v[208:211], v[32:35]
	v_mfma_f32_16x16x32_bf16 v[20:23], v[184:187], v[216:219], v[20:23]
	v_mfma_f32_16x16x32_bf16 v[16:19], v[192:195], v[216:219], v[16:19]
	v_mfma_f32_16x16x32_bf16 v[4:7], v[184:187], v[224:227], v[4:7]
	v_mfma_f32_16x16x32_bf16 v[0:3], v[192:195], v[224:227], v[0:3]
	s_setprio 0
	s_barrier
; #define PG8_STAGE(bufoff, gbase, voff) do { _Pragma("unroll") for (int _i = 0; _i < 2; ++_i) \
;         __builtin_amdgcn_global_load_lds((const unsigned*)((const char*)(gbase) + (voff)[_i]), (LAS unsigned*)(lds + (bufoff) + ldsw + _i * 8192), 16, 0, 0); } while (0)
; #define PG8_LDA(dst, b, h) do { _Pragma("unroll") for (int m = 0; m < 4; ++m) _Pragma("unroll") for (int k = 0; k < 2; ++k) dst[m][k] = *(const LAS bf16x8*)(lds + PG8_SA(b, h) + aoff + m * 2048 + k * 1024); } while (0)
; #define PG8_LDB(dst, b, h) do { _Pragma("unroll") for (int n = 0; n < 2; ++n) _Pragma("unroll") for (int k = 0; k < 2; ++k) dst[n][k] = *(const LAS bf16x8*)(lds + PG8_SB(b, h) + boff + n * 2048 + k * 1024); } while (0)
; #define PG8_MMA(ai, bj, At, Bt) do { __builtin_amdgcn_s_setprio(1); _Pragma("unroll") for (int m = 0; m < 4; ++m) _Pragma("unroll") for (int n = 0; n < 2; ++n) _Pragma("unroll") for (int k = 0; k < 2; ++k) \
;         acc[ai][bj][m][n] = __builtin_amdgcn_mfma_f32_16x16x32_bf16(Bt[n][k], At[m][k], acc[ai][bj][m][n], 0, 0, 0); __builtin_amdgcn_s_setprio(0); } while (0)
; #define PG8_WAIT_V(n) asm volatile("s_waitcnt vmcnt(" #n ")" ::: "memory")
; #define PG8_WAIT_L(n) asm volatile("s_waitcnt lgkmcnt(" #n ")" ::: "memory")
; #define PG8_BAR __builtin_amdgcn_s_barrier()
; #define PG8_SCHED __builtin_amdgcn_sched_barrier(0)
; template <class Epi>
; __device__ __forceinline__ void gemm_phase(LAS unsigned char* lds, const Gemm g, const StaticOrder& S, const Epi& E) {
;     ...
;             PG8_LDB(B0, 1, 0); PG8_LDB(B1, 1, 1); PG8_SCHED; PG8_LDA(At, 1, 0); PG8_STAGE(PG8_SA(0, 1), a2 + hsA, voffA);
;             PG8_WAIT_V(8); PG8_WAIT_L(0); PG8_BAR; PG8_MMA(0, 0, At, B0); PG8_MMA(0, 1, At, B1); PG8_BAR; PG8_SCHED;
;             PG8_LDA(At, 1, 1); PG8_STAGE(PG8_SB(1, 0), b3, voffB); PG8_STAGE(PG8_SB(1, 1), b3 + hsB, voffB); PG8_STAGE(PG8_SA(1, 0), a3, voffA);
;             PG8_WAIT_V(8); PG8_WAIT_L(0); PG8_BAR; PG8_MMA(1, 0, At, B0); PG8_MMA(1, 1, At, B1); PG8_BAR; PG8_SCHED;
;         }
	s_add_i32 s40, 0, 0x18000
	v_add_u32_e32 v159, s40, v153
	s_add_i32 s41, 0, 0x1c000
	ds_read_b128 v[144:147], v159
	ds_read_b128 v[148:151], v159 offset:1024
	ds_read_b128 v[162:165], v159 offset:2048
	ds_read_b128 v[166:169], v159 offset:3072
	v_add_u32_e32 v159, s41, v153
	ds_read_b128 v[180:183], v159
	ds_read_b128 v[184:187], v159 offset:1024
	ds_read_b128 v[188:191], v159 offset:2048
	ds_read_b128 v[192:195], v159 offset:3072
	s_add_u32 s38, s62, 0x40000
	s_addc_u32 s39, s63, 0
	s_mov_b32 m0, s23
	ds_read_b128 v[196:199], v157 offset:32768
	ds_read_b128 v[200:203], v157 offset:33792
	ds_read_b128 v[204:207], v157 offset:34816
	ds_read_b128 v[208:211], v157 offset:35840
	ds_read_b128 v[212:215], v157 offset:36864
	ds_read_b128 v[216:219], v157 offset:37888
	ds_read_b128 v[220:223], v157 offset:38912
	ds_read_b128 v[224:227], v157 offset:39936
	global_load_lds_dwordx4 v134, s[38:39]
	s_mov_b32 m0, s24
	s_nop 0
	global_load_lds_dwordx4 v130, s[38:39]
	s_waitcnt vmcnt(8)
	s_waitcnt lgkmcnt(0)
	s_barrier
	s_setprio 1
	s_waitcnt lgkmcnt(0)
	v_mfma_f32_16x16x32_bf16 v[124:127], v[144:147], v[196:199], v[124:127]
	v_mfma_f32_16x16x32_bf16 v[120:123], v[162:165], v[196:199], v[120:123]
	v_mfma_f32_16x16x32_bf16 v[108:111], v[144:147], v[204:207], v[108:111]
	v_mfma_f32_16x16x32_bf16 v[104:107], v[162:165], v[204:207], v[104:107]
	v_mfma_f32_16x16x32_bf16 v[92:95], v[144:147], v[212:215], v[92:95]
	v_mfma_f32_16x16x32_bf16 v[88:91], v[162:165], v[212:215], v[88:91]
	v_mfma_f32_16x16x32_bf16 v[76:79], v[144:147], v[220:223], v[76:79]
	v_mfma_f32_16x16x32_bf16 v[72:75], v[162:165], v[220:223], v[72:75]
	v_mfma_f32_16x16x32_bf16 v[124:127], v[148:151], v[200:203], v[124:127]
	v_mfma_f32_16x16x32_bf16 v[120:123], v[166:169], v[200:203], v[120:123]
	v_mfma_f32_16x16x32_bf16 v[108:111], v[148:151], v[208:211], v[108:111]
	v_mfma_f32_16x16x32_bf16 v[104:107], v[166:169], v[208:211], v[104:107]
	v_mfma_f32_16x16x32_bf16 v[92:95], v[148:151], v[216:219], v[92:95]
	v_mfma_f32_16x16x32_bf16 v[88:91], v[166:169], v[216:219], v[88:91]
	v_mfma_f32_16x16x32_bf16 v[76:79], v[148:151], v[224:227], v[76:79]
	v_mfma_f32_16x16x32_bf16 v[72:75], v[166:169], v[224:227], v[72:75]
	s_setprio 0
	s_setprio 1
	v_mfma_f32_16x16x32_bf16 v[116:119], v[180:183], v[196:199], v[116:119]
	v_mfma_f32_16x16x32_bf16 v[112:115], v[188:191], v[196:199], v[112:115]
	v_mfma_f32_16x16x32_bf16 v[100:103], v[180:183], v[204:207], v[100:103]
	v_mfma_f32_16x16x32_bf16 v[96:99], v[188:191], v[204:207], v[96:99]
	v_mfma_f32_16x16x32_bf16 v[84:87], v[180:183], v[212:215], v[84:87]
	v_mfma_f32_16x16x32_bf16 v[80:83], v[188:191], v[212:215], v[80:83]
	v_mfma_f32_16x16x32_bf16 v[68:71], v[180:183], v[220:223], v[68:71]
	v_mfma_f32_16x16x32_bf16 v[64:67], v[188:191], v[220:223], v[64:67]
	v_mfma_f32_16x16x32_bf16 v[116:119], v[184:187], v[200:203], v[116:119]
	v_mfma_f32_16x16x32_bf16 v[112:115], v[192:195], v[200:203], v[112:115]
	v_mfma_f32_16x16x32_bf16 v[100:103], v[184:187], v[208:211], v[100:103]
	v_mfma_f32_16x16x32_bf16 v[96:99], v[192:195], v[208:211], v[96:99]
	v_mfma_f32_16x16x32_bf16 v[84:87], v[184:187], v[216:219], v[84:87]
	v_mfma_f32_16x16x32_bf16 v[80:83], v[192:195], v[216:219], v[80:83]
	v_mfma_f32_16x16x32_bf16 v[68:71], v[184:187], v[224:227], v[68:71]
	v_mfma_f32_16x16x32_bf16 v[64:67], v[192:195], v[224:227], v[64:67]
	s_setprio 0
	s_barrier
	s_add_u32 s98, s60, 0x80
	s_addc_u32 s99, s61, 0
	s_add_u32 s100, s62, 0x80
	s_addc_u32 s101, s63, 0
	s_add_i32 s38, s40, s16
	s_mov_b32 m0, s38
	ds_read_b128 v[196:199], v157 offset:49152
	ds_read_b128 v[200:203], v157 offset:50176
	ds_read_b128 v[204:207], v157 offset:51200
	ds_read_b128 v[208:211], v157 offset:52224
	ds_read_b128 v[212:215], v157 offset:53248
	ds_read_b128 v[216:219], v157 offset:54272
	ds_read_b128 v[220:223], v157 offset:55296
	ds_read_b128 v[224:227], v157 offset:56320
	global_load_lds_dwordx4 v132, s[98:99]
	s_add_i32 m0, s38, 0x2000
	s_add_u32 s38, s60, 0x40080
	s_addc_u32 s39, s61, 0
	s_add_i32 s40, s41, s16
	global_load_lds_dwordx4 v128, s[98:99]
	s_mov_b32 m0, s40
	s_nop 0
	global_load_lds_dwordx4 v132, s[38:39]
	s_add_i32 m0, s40, 0x2000
	s_nop 0
	global_load_lds_dwordx4 v128, s[38:39]
	s_mov_b32 m0, s25
	s_nop 0
	global_load_lds_dwordx4 v134, s[100:101]
	s_mov_b32 m0, s26
	s_nop 0
	global_load_lds_dwordx4 v130, s[100:101]
	s_waitcnt vmcnt(8)
	s_waitcnt lgkmcnt(0)
	s_barrier
	s_setprio 1
	s_waitcnt lgkmcnt(0)
	v_mfma_f32_16x16x32_bf16 v[60:63], v[144:147], v[196:199], v[60:63]
	v_mfma_f32_16x16x32_bf16 v[56:59], v[162:165], v[196:199], v[56:59]
	v_mfma_f32_16x16x32_bf16 v[44:47], v[144:147], v[204:207], v[44:47]
	v_mfma_f32_16x16x32_bf16 v[40:43], v[162:165], v[204:207], v[40:43]
	v_mfma_f32_16x16x32_bf16 v[28:31], v[144:147], v[212:215], v[28:31]
	v_mfma_f32_16x16x32_bf16 v[24:27], v[162:165], v[212:215], v[24:27]
	v_mfma_f32_16x16x32_bf16 v[12:15], v[144:147], v[220:223], v[12:15]
	v_mfma_f32_16x16x32_bf16 v[8:11], v[162:165], v[220:223], v[8:11]
	v_mfma_f32_16x16x32_bf16 v[60:63], v[148:151], v[200:203], v[60:63]
	v_mfma_f32_16x16x32_bf16 v[56:59], v[166:169], v[200:203], v[56:59]
	v_mfma_f32_16x16x32_bf16 v[44:47], v[148:151], v[208:211], v[44:47]
	v_mfma_f32_16x16x32_bf16 v[40:43], v[166:169], v[208:211], v[40:43]
	v_mfma_f32_16x16x32_bf16 v[28:31], v[148:151], v[216:219], v[28:31]
	v_mfma_f32_16x16x32_bf16 v[24:27], v[166:169], v[216:219], v[24:27]
	v_mfma_f32_16x16x32_bf16 v[12:15], v[148:151], v[224:227], v[12:15]
	v_mfma_f32_16x16x32_bf16 v[8:11], v[166:169], v[224:227], v[8:11]
	s_setprio 0
	s_setprio 1
	v_mfma_f32_16x16x32_bf16 v[52:55], v[180:183], v[196:199], v[52:55]
	v_mfma_f32_16x16x32_bf16 v[48:51], v[188:191], v[196:199], v[48:51]
	v_mfma_f32_16x16x32_bf16 v[36:39], v[180:183], v[204:207], v[36:39]
	v_mfma_f32_16x16x32_bf16 v[32:35], v[188:191], v[204:207], v[32:35]
	v_mfma_f32_16x16x32_bf16 v[20:23], v[180:183], v[212:215], v[20:23]
	v_mfma_f32_16x16x32_bf16 v[16:19], v[188:191], v[212:215], v[16:19]
	v_mfma_f32_16x16x32_bf16 v[4:7], v[180:183], v[220:223], v[4:7]
	v_mfma_f32_16x16x32_bf16 v[0:3], v[188:191], v[220:223], v[0:3]
	v_mfma_f32_16x16x32_bf16 v[52:55], v[184:187], v[200:203], v[52:55]
	v_mfma_f32_16x16x32_bf16 v[48:51], v[192:195], v[200:203], v[48:51]
	v_mfma_f32_16x16x32_bf16 v[36:39], v[184:187], v[208:211], v[36:39]
	v_mfma_f32_16x16x32_bf16 v[32:35], v[192:195], v[208:211], v[32:35]
	v_mfma_f32_16x16x32_bf16 v[20:23], v[184:187], v[216:219], v[20:23]
	v_mfma_f32_16x16x32_bf16 v[16:19], v[192:195], v[216:219], v[16:19]
	v_mfma_f32_16x16x32_bf16 v[4:7], v[184:187], v[224:227], v[4:7]
	v_mfma_f32_16x16x32_bf16 v[0:3], v[192:195], v[224:227], v[0:3]
	s_setprio 0
	s_barrier
	s_add_i32 s37, s37, 2
	s_add_u32 s58, s58, 0x100
	s_addc_u32 s59, s59, 0
	s_add_u32 s35, s35, 0x100
	s_addc_u32 s36, s36, 0
	s_cmp_gt_u32 s37, 13
	s_cbranch_scc0 .LBB0_214
	s_and_b64 vcc, exec, s[8:9]
	s_cbranch_vccz .LBB0_217
	s_barrier

; #define PG8_STAGE(bufoff, gbase, voff) do { _Pragma("unroll") for (int _i = 0; _i < 2; ++_i) \
;         __builtin_amdgcn_global_load_lds((const unsigned*)((const char*)(gbase) + (voff)[_i]), (LAS unsigned*)(lds + (bufoff) + ldsw + _i * 8192), 16, 0, 0); } while (0)
; #define PG8_LDA(dst, b, h) do { _Pragma("unroll") for (int m = 0; m < 4; ++m) _Pragma("unroll") for (int k = 0; k < 2; ++k) dst[m][k] = *(const LAS bf16x8*)(lds + PG8_SA(b, h) + aoff + m * 2048 + k * 1024); } while (0)
; #define PG8_LDB(dst, b, h) do { _Pragma("unroll") for (int n = 0; n < 2; ++n) _Pragma("unroll") for (int k = 0; k < 2; ++k) dst[n][k] = *(const LAS bf16x8*)(lds + PG8_SB(b, h) + boff + n * 2048 + k * 1024); } while (0)
; #define PG8_MMA(ai, bj, At, Bt) do { __builtin_amdgcn_s_setprio(1); _Pragma("unroll") for (int m = 0; m < 4; ++m) _Pragma("unroll") for (int n = 0; n < 2; ++n) _Pragma("unroll") for (int k = 0; k < 2; ++k) \
;         acc[ai][bj][m][n] = __builtin_amdgcn_mfma_f32_16x16x32_bf16(Bt[n][k], At[m][k], acc[ai][bj][m][n], 0, 0, 0); __builtin_amdgcn_s_setprio(0); } while (0)
; #define PG8_WAIT_V(n) asm volatile("s_waitcnt vmcnt(" #n ")" ::: "memory")
; template <class Epi>
; __device__ __forceinline__ void gemm_phase(LAS unsigned char* lds, const Gemm g, const StaticOrder& S, const Epi& E) {
;     ...
;         for (int t = 0; t < nt; t += 2) {
;             const bool last = (t == nt - 2);
;             if constexpr (Epi::HAS_MID) { if (t == nt1) E.mid(acc, cur, wr, wc, fr, fq); }
;             const char* a1 = cA + ((Epi::HAS_MID && t >= nt1) ? dA2 : 0) + (size_t)(t + 1) * kstep;
;             const char* a2 = last ? nA : cA + ((Epi::HAS_MID && t + 2 >= nt1) ? dA2 : 0) + (size_t)(t + 2) * kstep; const char* b2 = last ? nB : cB + ((Epi::HAS_MID && t + 2 >= nt1) ? dB2 : 0) + (size_t)(t + 2) * kstep;
;             const char* a3 = a2 + kstep; const char* b3 = b2 + kstep;
;             PG8_LDB(B0, 0, 0); PG8_LDB(B1, 0, 1); PG8_SCHED; PG8_LDA(At, 0, 0); PG8_STAGE(PG8_SA(1, 1), a1 + hsA, voffA);
;             PG8_WAIT_V(8); PG8_WAIT_L(0); PG8_BAR; PG8_MMA(0, 0, At, B0); PG8_MMA(0, 1, At, B1); PG8_BAR; PG8_SCHED;
;             PG8_LDA(At, 0, 1); PG8_STAGE(PG8_SB(0, 0), b2, voffB); PG8_STAGE(PG8_SB(0, 1), b2 + hsB, voffB); PG8_STAGE(PG8_SA(0, 0), a2, voffA);
;             PG8_WAIT_V(8); PG8_WAIT_L(0); PG8_BAR; PG8_MMA(1, 0, At, B0); PG8_MMA(1, 1, At, B1); PG8_BAR; PG8_SCHED;
.LBB0_296:
	ds_read_b128 v[144:147], v157
	ds_read_b128 v[148:151], v157 offset:1024
	ds_read_b128 v[164:167], v157 offset:2048
	ds_read_b128 v[168:171], v157 offset:3072
	ds_read_b128 v[180:183], v158
	ds_read_b128 v[184:187], v158 offset:1024
	ds_read_b128 v[188:191], v158 offset:2048
	ds_read_b128 v[192:195], v158 offset:3072
	s_add_u32 s60, s12, 0x100
	s_addc_u32 s61, s13, 0
	s_cmp_eq_u32 s34, 40
	s_cselect_b32 s65, s1, s61
	s_cselect_b32 s64, s0, s60
	s_cselect_b32 s63, s59, s7
	s_cselect_b32 s62, s58, s6
	s_add_i32 m0, s5, 0xc000
	ds_read_b128 v[196:199], v159
	ds_read_b128 v[200:203], v159 offset:1024
	ds_read_b128 v[204:207], v159 offset:2048
	ds_read_b128 v[208:211], v159 offset:3072
	ds_read_b128 v[212:215], v159 offset:4096
	ds_read_b128 v[216:219], v159 offset:5120
	ds_read_b128 v[220:223], v159 offset:6144
	ds_read_b128 v[224:227], v159 offset:7168
	global_load_lds_dwordx4 v136, s[12:13]
	s_add_i32 m0, s5, 0xe000
	s_nop 0
	global_load_lds_dwordx4 v138, s[12:13]
	s_waitcnt vmcnt(8)
	s_waitcnt lgkmcnt(0)
	s_barrier
	s_setprio 1
	s_waitcnt lgkmcnt(0)
	v_mfma_f32_16x16x32_bf16 v[124:127], v[144:147], v[196:199], v[124:127]
	v_mfma_f32_16x16x32_bf16 v[120:123], v[164:167], v[196:199], v[120:123]
	v_mfma_f32_16x16x32_bf16 v[108:111], v[144:147], v[204:207], v[108:111]
	v_mfma_f32_16x16x32_bf16 v[104:107], v[164:167], v[204:207], v[104:107]
	v_mfma_f32_16x16x32_bf16 v[92:95], v[144:147], v[212:215], v[92:95]
	v_mfma_f32_16x16x32_bf16 v[88:91], v[164:167], v[212:215], v[88:91]
	v_mfma_f32_16x16x32_bf16 v[76:79], v[144:147], v[220:223], v[76:79]
	v_mfma_f32_16x16x32_bf16 v[72:75], v[164:167], v[220:223], v[72:75]
	v_mfma_f32_16x16x32_bf16 v[124:127], v[148:151], v[200:203], v[124:127]
	v_mfma_f32_16x16x32_bf16 v[120:123], v[168:171], v[200:203], v[120:123]
	v_mfma_f32_16x16x32_bf16 v[108:111], v[148:151], v[208:211], v[108:111]
	v_mfma_f32_16x16x32_bf16 v[104:107], v[168:171], v[208:211], v[104:107]
	v_mfma_f32_16x16x32_bf16 v[92:95], v[148:151], v[216:219], v[92:95]
	v_mfma_f32_16x16x32_bf16 v[88:91], v[168:171], v[216:219], v[88:91]
	v_mfma_f32_16x16x32_bf16 v[76:79], v[148:151], v[224:227], v[76:79]
	v_mfma_f32_16x16x32_bf16 v[72:75], v[168:171], v[224:227], v[72:75]
	s_setprio 0
	s_setprio 1
	v_mfma_f32_16x16x32_bf16 v[116:119], v[180:183], v[196:199], v[116:119]
	v_mfma_f32_16x16x32_bf16 v[112:115], v[188:191], v[196:199], v[112:115]
	v_mfma_f32_16x16x32_bf16 v[100:103], v[180:183], v[204:207], v[100:103]
	v_mfma_f32_16x16x32_bf16 v[96:99], v[188:191], v[204:207], v[96:99]
	v_mfma_f32_16x16x32_bf16 v[84:87], v[180:183], v[212:215], v[84:87]
	v_mfma_f32_16x16x32_bf16 v[80:83], v[188:191], v[212:215], v[80:83]
	v_mfma_f32_16x16x32_bf16 v[68:71], v[180:183], v[220:223], v[68:71]
	v_mfma_f32_16x16x32_bf16 v[64:67], v[188:191], v[220:223], v[64:67]
	v_mfma_f32_16x16x32_bf16 v[116:119], v[184:187], v[200:203], v[116:119]
	v_mfma_f32_16x16x32_bf16 v[112:115], v[192:195], v[200:203], v[112:115]
	v_mfma_f32_16x16x32_bf16 v[100:103], v[184:187], v[208:211], v[100:103]
	v_mfma_f32_16x16x32_bf16 v[96:99], v[192:195], v[208:211], v[96:99]
	v_mfma_f32_16x16x32_bf16 v[84:87], v[184:187], v[216:219], v[84:87]
	v_mfma_f32_16x16x32_bf16 v[80:83], v[192:195], v[216:219], v[80:83]
	v_mfma_f32_16x16x32_bf16 v[68:71], v[184:187], v[224:227], v[68:71]
	v_mfma_f32_16x16x32_bf16 v[64:67], v[192:195], v[224:227], v[64:67]
	s_setprio 0
	s_barrier
	s_add_i32 s12, s27, s4
	s_mov_b32 m0, s12
	ds_read_b128 v[196:199], v159 offset:16384
	ds_read_b128 v[200:203], v159 offset:17408
	ds_read_b128 v[204:207], v159 offset:18432
	ds_read_b128 v[208:211], v159 offset:19456
	ds_read_b128 v[212:215], v159 offset:20480
	ds_read_b128 v[216:219], v159 offset:21504
	ds_read_b128 v[220:223], v159 offset:22528
	ds_read_b128 v[224:227], v159 offset:23552
	global_load_lds_dwordx4 v130, s[62:63]
	s_add_i32 m0, s12, 0x2000
	s_add_u32 s12, s62, 0xb0000
	s_addc_u32 s13, s63, 0
	s_add_i32 s35, s28, s4
	global_load_lds_dwordx4 v134, s[62:63]
	s_mov_b32 m0, s35
	s_nop 0
	global_load_lds_dwordx4 v130, s[12:13]
	s_add_i32 m0, s35, 0x2000
	s_nop 0
	global_load_lds_dwordx4 v134, s[12:13]
	s_mov_b32 m0, s5
	s_nop 0
	global_load_lds_dwordx4 v128, s[64:65]
	s_mov_b32 m0, s16
	s_nop 0
	global_load_lds_dwordx4 v132, s[64:65]
	s_waitcnt vmcnt(8)
	s_waitcnt lgkmcnt(0)
	s_barrier
	s_setprio 1
	s_waitcnt lgkmcnt(0)
	v_mfma_f32_16x16x32_bf16 v[60:63], v[144:147], v[196:199], v[60:63]
	v_mfma_f32_16x16x32_bf16 v[56:59], v[164:167], v[196:199], v[56:59]
	v_mfma_f32_16x16x32_bf16 v[44:47], v[144:147], v[204:207], v[44:47]
	v_mfma_f32_16x16x32_bf16 v[40:43], v[164:167], v[204:207], v[40:43]
	v_mfma_f32_16x16x32_bf16 v[28:31], v[144:147], v[212:215], v[28:31]
	v_mfma_f32_16x16x32_bf16 v[24:27], v[164:167], v[212:215], v[24:27]
	v_mfma_f32_16x16x32_bf16 v[12:15], v[144:147], v[220:223], v[12:15]
	v_mfma_f32_16x16x32_bf16 v[8:11], v[164:167], v[220:223], v[8:11]
	v_mfma_f32_16x16x32_bf16 v[60:63], v[148:151], v[200:203], v[60:63]
	v_mfma_f32_16x16x32_bf16 v[56:59], v[168:171], v[200:203], v[56:59]
	v_mfma_f32_16x16x32_bf16 v[44:47], v[148:151], v[208:211], v[44:47]
	v_mfma_f32_16x16x32_bf16 v[40:43], v[168:171], v[208:211], v[40:43]
	v_mfma_f32_16x16x32_bf16 v[28:31], v[148:151], v[216:219], v[28:31]
	v_mfma_f32_16x16x32_bf16 v[24:27], v[168:171], v[216:219], v[24:27]
	v_mfma_f32_16x16x32_bf16 v[12:15], v[148:151], v[224:227], v[12:15]
	v_mfma_f32_16x16x32_bf16 v[8:11], v[168:171], v[224:227], v[8:11]
	s_setprio 0
	s_setprio 1
	v_mfma_f32_16x16x32_bf16 v[52:55], v[180:183], v[196:199], v[52:55]
	v_mfma_f32_16x16x32_bf16 v[48:51], v[188:191], v[196:199], v[48:51]
	v_mfma_f32_16x16x32_bf16 v[36:39], v[180:183], v[204:207], v[36:39]
	v_mfma_f32_16x16x32_bf16 v[32:35], v[188:191], v[204:207], v[32:35]
	v_mfma_f32_16x16x32_bf16 v[20:23], v[180:183], v[212:215], v[20:23]
	v_mfma_f32_16x16x32_bf16 v[16:19], v[188:191], v[212:215], v[16:19]
	v_mfma_f32_16x16x32_bf16 v[4:7], v[180:183], v[220:223], v[4:7]
	v_mfma_f32_16x16x32_bf16 v[0:3], v[188:191], v[220:223], v[0:3]
	v_mfma_f32_16x16x32_bf16 v[52:55], v[184:187], v[200:203], v[52:55]
	v_mfma_f32_16x16x32_bf16 v[48:51], v[192:195], v[200:203], v[48:51]
	v_mfma_f32_16x16x32_bf16 v[36:39], v[184:187], v[208:211], v[36:39]
	v_mfma_f32_16x16x32_bf16 v[32:35], v[192:195], v[208:211], v[32:35]
	v_mfma_f32_16x16x32_bf16 v[20:23], v[184:187], v[216:219], v[20:23]
	v_mfma_f32_16x16x32_bf16 v[16:19], v[192:195], v[216:219], v[16:19]
	v_mfma_f32_16x16x32_bf16 v[4:7], v[184:187], v[224:227], v[4:7]
	v_mfma_f32_16x16x32_bf16 v[0:3], v[192:195], v[224:227], v[0:3]
	s_setprio 0
	s_barrier
; #define PG8_STAGE(bufoff, gbase, voff) do { _Pragma("unroll") for (int _i = 0; _i < 2; ++_i) \
;         __builtin_amdgcn_global_load_lds((const unsigned*)((const char*)(gbase) + (voff)[_i]), (LAS unsigned*)(lds + (bufoff) + ldsw + _i * 8192), 16, 0, 0); } while (0)
; #define PG8_LDA(dst, b, h) do { _Pragma("unroll") for (int m = 0; m < 4; ++m) _Pragma("unroll") for (int k = 0; k < 2; ++k) dst[m][k] = *(const LAS bf16x8*)(lds + PG8_SA(b, h) + aoff + m * 2048 + k * 1024); } while (0)
; #define PG8_LDB(dst, b, h) do { _Pragma("unroll") for (int n = 0; n < 2; ++n) _Pragma("unroll") for (int k = 0; k < 2; ++k) dst[n][k] = *(const LAS bf16x8*)(lds + PG8_SB(b, h) + boff + n * 2048 + k * 1024); } while (0)
; #define PG8_MMA(ai, bj, At, Bt) do { __builtin_amdgcn_s_setprio(1); _Pragma("unroll") for (int m = 0; m < 4; ++m) _Pragma("unroll") for (int n = 0; n < 2; ++n) _Pragma("unroll") for (int k = 0; k < 2; ++k) \
;         acc[ai][bj][m][n] = __builtin_amdgcn_mfma_f32_16x16x32_bf16(Bt[n][k], At[m][k], acc[ai][bj][m][n], 0, 0, 0); __builtin_amdgcn_s_setprio(0); } while (0)
; #define PG8_WAIT_V(n) asm volatile("s_waitcnt vmcnt(" #n ")" ::: "memory")
; #define PG8_WAIT_L(n) asm volatile("s_waitcnt lgkmcnt(" #n ")" ::: "memory")
; #define PG8_BAR __builtin_amdgcn_s_barrier()
; #define PG8_SCHED __builtin_amdgcn_sched_barrier(0)
; template <class Epi>
; __device__ __forceinline__ void gemm_phase(LAS unsigned char* lds, const Gemm g, const StaticOrder& S, const Epi& E) {
;     ...
;             PG8_LDB(B0, 1, 0); PG8_LDB(B1, 1, 1); PG8_SCHED; PG8_LDA(At, 1, 0); PG8_STAGE(PG8_SA(0, 1), a2 + hsA, voffA);
;             PG8_WAIT_V(8); PG8_WAIT_L(0); PG8_BAR; PG8_MMA(0, 0, At, B0); PG8_MMA(0, 1, At, B1); PG8_BAR; PG8_SCHED;
;             PG8_LDA(At, 1, 1); PG8_STAGE(PG8_SB(1, 0), b3, voffB); PG8_STAGE(PG8_SB(1, 1), b3 + hsB, voffB); PG8_STAGE(PG8_SA(1, 0), a3, voffA);
;             PG8_WAIT_V(8); PG8_WAIT_L(0); PG8_BAR; PG8_MMA(1, 0, At, B0); PG8_MMA(1, 1, At, B1); PG8_BAR; PG8_SCHED;
;         }
	s_add_i32 s35, 0, 0x18000
	v_add_u32_e32 v163, s35, v155
	s_add_i32 s36, 0, 0x1c000
	ds_read_b128 v[144:147], v163
	ds_read_b128 v[148:151], v163 offset:1024
	ds_read_b128 v[164:167], v163 offset:2048
	ds_read_b128 v[168:171], v163 offset:3072
	v_add_u32_e32 v163, s36, v155
	ds_read_b128 v[180:183], v163
	ds_read_b128 v[184:187], v163 offset:1024
	ds_read_b128 v[188:191], v163 offset:2048
	ds_read_b128 v[192:195], v163 offset:3072
	s_add_u32 s12, s64, 0xb0000
	s_addc_u32 s13, s65, 0
	s_mov_b32 m0, s17
	ds_read_b128 v[196:199], v159 offset:32768
	ds_read_b128 v[200:203], v159 offset:33792
	ds_read_b128 v[204:207], v159 offset:34816
	ds_read_b128 v[208:211], v159 offset:35840
	ds_read_b128 v[212:215], v159 offset:36864
	ds_read_b128 v[216:219], v159 offset:37888
	ds_read_b128 v[220:223], v159 offset:38912
	ds_read_b128 v[224:227], v159 offset:39936
	global_load_lds_dwordx4 v128, s[12:13]
	s_mov_b32 m0, s18
	s_nop 0
	global_load_lds_dwordx4 v132, s[12:13]
	s_waitcnt vmcnt(8)
	s_waitcnt lgkmcnt(0)
	s_barrier
	s_setprio 1
	s_waitcnt lgkmcnt(0)
	v_mfma_f32_16x16x32_bf16 v[124:127], v[144:147], v[196:199], v[124:127]
	v_mfma_f32_16x16x32_bf16 v[120:123], v[164:167], v[196:199], v[120:123]
	v_mfma_f32_16x16x32_bf16 v[108:111], v[144:147], v[204:207], v[108:111]
	v_mfma_f32_16x16x32_bf16 v[104:107], v[164:167], v[204:207], v[104:107]
	v_mfma_f32_16x16x32_bf16 v[92:95], v[144:147], v[212:215], v[92:95]
	v_mfma_f32_16x16x32_bf16 v[88:91], v[164:167], v[212:215], v[88:91]
	v_mfma_f32_16x16x32_bf16 v[76:79], v[144:147], v[220:223], v[76:79]
	v_mfma_f32_16x16x32_bf16 v[72:75], v[164:167], v[220:223], v[72:75]
	v_mfma_f32_16x16x32_bf16 v[124:127], v[148:151], v[200:203], v[124:127]
	v_mfma_f32_16x16x32_bf16 v[120:123], v[168:171], v[200:203], v[120:123]
	v_mfma_f32_16x16x32_bf16 v[108:111], v[148:151], v[208:211], v[108:111]
	v_mfma_f32_16x16x32_bf16 v[104:107], v[168:171], v[208:211], v[104:107]
	v_mfma_f32_16x16x32_bf16 v[92:95], v[148:151], v[216:219], v[92:95]
	v_mfma_f32_16x16x32_bf16 v[88:91], v[168:171], v[216:219], v[88:91]
	v_mfma_f32_16x16x32_bf16 v[76:79], v[148:151], v[224:227], v[76:79]
	v_mfma_f32_16x16x32_bf16 v[72:75], v[168:171], v[224:227], v[72:75]
	s_setprio 0
	s_setprio 1
	v_mfma_f32_16x16x32_bf16 v[116:119], v[180:183], v[196:199], v[116:119]
	v_mfma_f32_16x16x32_bf16 v[112:115], v[188:191], v[196:199], v[112:115]
	v_mfma_f32_16x16x32_bf16 v[100:103], v[180:183], v[204:207], v[100:103]
	v_mfma_f32_16x16x32_bf16 v[96:99], v[188:191], v[204:207], v[96:99]
	v_mfma_f32_16x16x32_bf16 v[84:87], v[180:183], v[212:215], v[84:87]
	v_mfma_f32_16x16x32_bf16 v[80:83], v[188:191], v[212:215], v[80:83]
	v_mfma_f32_16x16x32_bf16 v[68:71], v[180:183], v[220:223], v[68:71]
	v_mfma_f32_16x16x32_bf16 v[64:67], v[188:191], v[220:223], v[64:67]
	v_mfma_f32_16x16x32_bf16 v[116:119], v[184:187], v[200:203], v[116:119]
	v_mfma_f32_16x16x32_bf16 v[112:115], v[192:195], v[200:203], v[112:115]
	v_mfma_f32_16x16x32_bf16 v[100:103], v[184:187], v[208:211], v[100:103]
	v_mfma_f32_16x16x32_bf16 v[96:99], v[192:195], v[208:211], v[96:99]
	v_mfma_f32_16x16x32_bf16 v[84:87], v[184:187], v[216:219], v[84:87]
	v_mfma_f32_16x16x32_bf16 v[80:83], v[192:195], v[216:219], v[80:83]
	v_mfma_f32_16x16x32_bf16 v[68:71], v[184:187], v[224:227], v[68:71]
	v_mfma_f32_16x16x32_bf16 v[64:67], v[192:195], v[224:227], v[64:67]
	s_setprio 0
	s_barrier
	s_add_u32 s98, s62, 0x80
	s_addc_u32 s99, s63, 0
	s_add_u32 s100, s64, 0x80
	s_addc_u32 s101, s65, 0
	s_add_i32 s12, s35, s4
	s_mov_b32 m0, s12
	ds_read_b128 v[196:199], v159 offset:49152
	ds_read_b128 v[200:203], v159 offset:50176
	ds_read_b128 v[204:207], v159 offset:51200
	ds_read_b128 v[208:211], v159 offset:52224
	ds_read_b128 v[212:215], v159 offset:53248
	ds_read_b128 v[216:219], v159 offset:54272
	ds_read_b128 v[220:223], v159 offset:55296
	ds_read_b128 v[224:227], v159 offset:56320
	global_load_lds_dwordx4 v130, s[98:99]
	s_add_i32 m0, s12, 0x2000
	s_add_u32 s12, s62, 0xb0080
	s_addc_u32 s13, s63, 0
	s_add_i32 s35, s36, s4
	global_load_lds_dwordx4 v134, s[98:99]
	s_mov_b32 m0, s35
	s_nop 0
	global_load_lds_dwordx4 v130, s[12:13]
	s_add_i32 m0, s35, 0x2000
	s_nop 0
	global_load_lds_dwordx4 v134, s[12:13]
	s_mov_b32 m0, s22
	s_nop 0
	global_load_lds_dwordx4 v128, s[100:101]
	s_mov_b32 m0, s23
	s_nop 0
	global_load_lds_dwordx4 v132, s[100:101]
	s_waitcnt vmcnt(8)
	s_waitcnt lgkmcnt(0)
	s_barrier
	s_setprio 1
	s_waitcnt lgkmcnt(0)
	v_mfma_f32_16x16x32_bf16 v[60:63], v[144:147], v[196:199], v[60:63]
	v_mfma_f32_16x16x32_bf16 v[56:59], v[164:167], v[196:199], v[56:59]
	v_mfma_f32_16x16x32_bf16 v[44:47], v[144:147], v[204:207], v[44:47]
	v_mfma_f32_16x16x32_bf16 v[40:43], v[164:167], v[204:207], v[40:43]
	v_mfma_f32_16x16x32_bf16 v[28:31], v[144:147], v[212:215], v[28:31]
	v_mfma_f32_16x16x32_bf16 v[24:27], v[164:167], v[212:215], v[24:27]
	v_mfma_f32_16x16x32_bf16 v[12:15], v[144:147], v[220:223], v[12:15]
	v_mfma_f32_16x16x32_bf16 v[8:11], v[164:167], v[220:223], v[8:11]
	v_mfma_f32_16x16x32_bf16 v[60:63], v[148:151], v[200:203], v[60:63]
	v_mfma_f32_16x16x32_bf16 v[56:59], v[168:171], v[200:203], v[56:59]
	v_mfma_f32_16x16x32_bf16 v[44:47], v[148:151], v[208:211], v[44:47]
	v_mfma_f32_16x16x32_bf16 v[40:43], v[168:171], v[208:211], v[40:43]
	v_mfma_f32_16x16x32_bf16 v[28:31], v[148:151], v[216:219], v[28:31]
	v_mfma_f32_16x16x32_bf16 v[24:27], v[168:171], v[216:219], v[24:27]
	v_mfma_f32_16x16x32_bf16 v[12:15], v[148:151], v[224:227], v[12:15]
	v_mfma_f32_16x16x32_bf16 v[8:11], v[168:171], v[224:227], v[8:11]
	s_setprio 0
	s_setprio 1
	v_mfma_f32_16x16x32_bf16 v[52:55], v[180:183], v[196:199], v[52:55]
	v_mfma_f32_16x16x32_bf16 v[48:51], v[188:191], v[196:199], v[48:51]
	v_mfma_f32_16x16x32_bf16 v[36:39], v[180:183], v[204:207], v[36:39]
	v_mfma_f32_16x16x32_bf16 v[32:35], v[188:191], v[204:207], v[32:35]
	v_mfma_f32_16x16x32_bf16 v[20:23], v[180:183], v[212:215], v[20:23]
	v_mfma_f32_16x16x32_bf16 v[16:19], v[188:191], v[212:215], v[16:19]
	v_mfma_f32_16x16x32_bf16 v[4:7], v[180:183], v[220:223], v[4:7]
	v_mfma_f32_16x16x32_bf16 v[0:3], v[188:191], v[220:223], v[0:3]
	v_mfma_f32_16x16x32_bf16 v[52:55], v[184:187], v[200:203], v[52:55]
	v_mfma_f32_16x16x32_bf16 v[48:51], v[192:195], v[200:203], v[48:51]
	v_mfma_f32_16x16x32_bf16 v[36:39], v[184:187], v[208:211], v[36:39]
	v_mfma_f32_16x16x32_bf16 v[32:35], v[192:195], v[208:211], v[32:35]
	v_mfma_f32_16x16x32_bf16 v[20:23], v[184:187], v[216:219], v[20:23]
	v_mfma_f32_16x16x32_bf16 v[16:19], v[192:195], v[216:219], v[16:19]
	v_mfma_f32_16x16x32_bf16 v[4:7], v[184:187], v[224:227], v[4:7]
	v_mfma_f32_16x16x32_bf16 v[0:3], v[192:195], v[224:227], v[0:3]
	s_setprio 0
	s_barrier
	s_add_i32 s34, s34, 2
	s_add_u32 s6, s6, 0x100
	s_addc_u32 s7, s7, 0
	s_cmp_gt_u32 s34, 41
	s_mov_b64 s[12:13], s[60:61]
	s_cbranch_scc0 .LBB0_296
	s_and_b64 vcc, exec, s[42:43]
	s_cbranch_vccz .LBB0_299
	s_barrier

; #define PG8_STAGE(bufoff, gbase, voff) do { _Pragma("unroll") for (int _i = 0; _i < 2; ++_i) \
;         __builtin_amdgcn_global_load_lds((const unsigned*)((const char*)(gbase) + (voff)[_i]), (LAS unsigned*)(lds + (bufoff) + ldsw + _i * 8192), 16, 0, 0); } while (0)
; #define PG8_LDA(dst, b, h) do { _Pragma("unroll") for (int m = 0; m < 4; ++m) _Pragma("unroll") for (int k = 0; k < 2; ++k) dst[m][k] = *(const LAS bf16x8*)(lds + PG8_SA(b, h) + aoff + m * 2048 + k * 1024); } while (0)
; #define PG8_LDB(dst, b, h) do { _Pragma("unroll") for (int n = 0; n < 2; ++n) _Pragma("unroll") for (int k = 0; k < 2; ++k) dst[n][k] = *(const LAS bf16x8*)(lds + PG8_SB(b, h) + boff + n * 2048 + k * 1024); } while (0)
; #define PG8_MMA(ai, bj, At, Bt) do { __builtin_amdgcn_s_setprio(1); _Pragma("unroll") for (int m = 0; m < 4; ++m) _Pragma("unroll") for (int n = 0; n < 2; ++n) _Pragma("unroll") for (int k = 0; k < 2; ++k) \
;         acc[ai][bj][m][n] = __builtin_amdgcn_mfma_f32_16x16x32_bf16(Bt[n][k], At[m][k], acc[ai][bj][m][n], 0, 0, 0); __builtin_amdgcn_s_setprio(0); } while (0)
; #define PG8_WAIT_V(n) asm volatile("s_waitcnt vmcnt(" #n ")" ::: "memory")
; template <class Epi>
; __device__ __forceinline__ void gemm_phase(LAS unsigned char* lds, const Gemm g, const StaticOrder& S, const Epi& E) {
;     ...
;         for (int t = 0; t < nt; t += 2) {
;             const bool last = (t == nt - 2);
;             if constexpr (Epi::HAS_MID) { if (t == nt1) E.mid(acc, cur, wr, wc, fr, fq); }
;             const char* a1 = cA + ((Epi::HAS_MID && t >= nt1) ? dA2 : 0) + (size_t)(t + 1) * kstep;
;             const char* a2 = last ? nA : cA + ((Epi::HAS_MID && t + 2 >= nt1) ? dA2 : 0) + (size_t)(t + 2) * kstep; const char* b2 = last ? nB : cB + ((Epi::HAS_MID && t + 2 >= nt1) ? dB2 : 0) + (size_t)(t + 2) * kstep;
;             const char* a3 = a2 + kstep; const char* b3 = b2 + kstep;
;             PG8_LDB(B0, 0, 0); PG8_LDB(B1, 0, 1); PG8_SCHED; PG8_LDA(At, 0, 0); PG8_STAGE(PG8_SA(1, 1), a1 + hsA, voffA);
;             PG8_WAIT_V(8); PG8_WAIT_L(0); PG8_BAR; PG8_MMA(0, 0, At, B0); PG8_MMA(0, 1, At, B1); PG8_BAR; PG8_SCHED;
;             PG8_LDA(At, 0, 1); PG8_STAGE(PG8_SB(0, 0), b2, voffB); PG8_STAGE(PG8_SB(0, 1), b2 + hsB, voffB); PG8_STAGE(PG8_SA(0, 0), a2, voffA);
;             PG8_WAIT_V(8); PG8_WAIT_L(0); PG8_BAR; PG8_MMA(1, 0, At, B0); PG8_MMA(1, 1, At, B1); PG8_BAR; PG8_SCHED;
.LBB0_414:
	ds_read_b128 v[152:155], v167
	ds_read_b128 v[156:159], v167 offset:1024
	ds_read_b128 v[162:165], v167 offset:2048
	ds_read_b128 v[180:183], v167 offset:3072
	ds_read_b128 v[184:187], v168
	ds_read_b128 v[188:191], v168 offset:1024
	ds_read_b128 v[192:195], v168 offset:2048
	ds_read_b128 v[196:199], v168 offset:3072
	s_add_u32 s12, s10, 0xfffc0080
	s_addc_u32 s13, s11, -1
	s_cmp_eq_u32 s17, 12
	s_cselect_b32 s87, s0, s13
	s_cselect_b32 s86, s2, s12
	s_cselect_b32 s13, s3, s15
	s_cselect_b32 s12, s6, s7
	s_add_i32 m0, s5, 0xc000
	ds_read_b128 v[200:203], v169
	ds_read_b128 v[204:207], v169 offset:1024
	ds_read_b128 v[208:211], v169 offset:2048
	ds_read_b128 v[212:215], v169 offset:3072
	ds_read_b128 v[216:219], v169 offset:4096
	ds_read_b128 v[220:223], v169 offset:5120
	ds_read_b128 v[224:227], v169 offset:6144
	ds_read_b128 v[228:231], v169 offset:7168
	global_load_lds_dwordx4 v144, s[10:11]
	s_add_i32 m0, s5, 0xe000
	s_nop 0
	global_load_lds_dwordx4 v146, s[10:11]
	s_waitcnt vmcnt(8)
	s_waitcnt lgkmcnt(0)
	s_barrier
	s_setprio 1
	s_waitcnt lgkmcnt(0)
	v_mfma_f32_16x16x32_bf16 v[124:127], v[152:155], v[200:203], v[124:127]
	v_mfma_f32_16x16x32_bf16 v[120:123], v[162:165], v[200:203], v[120:123]
	v_mfma_f32_16x16x32_bf16 v[108:111], v[152:155], v[208:211], v[108:111]
	v_mfma_f32_16x16x32_bf16 v[104:107], v[162:165], v[208:211], v[104:107]
	v_mfma_f32_16x16x32_bf16 v[92:95], v[152:155], v[216:219], v[92:95]
	v_mfma_f32_16x16x32_bf16 v[88:91], v[162:165], v[216:219], v[88:91]
	v_mfma_f32_16x16x32_bf16 v[76:79], v[152:155], v[224:227], v[76:79]
	v_mfma_f32_16x16x32_bf16 v[72:75], v[162:165], v[224:227], v[72:75]
	v_mfma_f32_16x16x32_bf16 v[124:127], v[156:159], v[204:207], v[124:127]
	v_mfma_f32_16x16x32_bf16 v[120:123], v[180:183], v[204:207], v[120:123]
	v_mfma_f32_16x16x32_bf16 v[108:111], v[156:159], v[212:215], v[108:111]
	v_mfma_f32_16x16x32_bf16 v[104:107], v[180:183], v[212:215], v[104:107]
	v_mfma_f32_16x16x32_bf16 v[92:95], v[156:159], v[220:223], v[92:95]
	v_mfma_f32_16x16x32_bf16 v[88:91], v[180:183], v[220:223], v[88:91]
	v_mfma_f32_16x16x32_bf16 v[76:79], v[156:159], v[228:231], v[76:79]
	v_mfma_f32_16x16x32_bf16 v[72:75], v[180:183], v[228:231], v[72:75]
	s_setprio 0
	s_setprio 1
	v_mfma_f32_16x16x32_bf16 v[116:119], v[184:187], v[200:203], v[116:119]
	v_mfma_f32_16x16x32_bf16 v[112:115], v[192:195], v[200:203], v[112:115]
	v_mfma_f32_16x16x32_bf16 v[100:103], v[184:187], v[208:211], v[100:103]
	v_mfma_f32_16x16x32_bf16 v[96:99], v[192:195], v[208:211], v[96:99]
	v_mfma_f32_16x16x32_bf16 v[84:87], v[184:187], v[216:219], v[84:87]
	v_mfma_f32_16x16x32_bf16 v[80:83], v[192:195], v[216:219], v[80:83]
	v_mfma_f32_16x16x32_bf16 v[68:71], v[184:187], v[224:227], v[68:71]
	v_mfma_f32_16x16x32_bf16 v[64:67], v[192:195], v[224:227], v[64:67]
	v_mfma_f32_16x16x32_bf16 v[116:119], v[188:191], v[204:207], v[116:119]
	v_mfma_f32_16x16x32_bf16 v[112:115], v[196:199], v[204:207], v[112:115]
	v_mfma_f32_16x16x32_bf16 v[100:103], v[188:191], v[212:215], v[100:103]
	v_mfma_f32_16x16x32_bf16 v[96:99], v[196:199], v[212:215], v[96:99]
	v_mfma_f32_16x16x32_bf16 v[84:87], v[188:191], v[220:223], v[84:87]
	v_mfma_f32_16x16x32_bf16 v[80:83], v[196:199], v[220:223], v[80:83]
	v_mfma_f32_16x16x32_bf16 v[68:71], v[188:191], v[228:231], v[68:71]
	v_mfma_f32_16x16x32_bf16 v[64:67], v[196:199], v[228:231], v[64:67]
	s_setprio 0
	s_barrier
	s_add_i32 s19, s65, s4
	s_mov_b32 m0, s19
	ds_read_b128 v[200:203], v169 offset:16384
	ds_read_b128 v[204:207], v169 offset:17408
	ds_read_b128 v[208:211], v169 offset:18432
	ds_read_b128 v[212:215], v169 offset:19456
	ds_read_b128 v[216:219], v169 offset:20480
	ds_read_b128 v[220:223], v169 offset:21504
	ds_read_b128 v[224:227], v169 offset:22528
	ds_read_b128 v[228:231], v169 offset:23552
	global_load_lds_dwordx4 v130, s[12:13]
	s_add_i32 m0, s19, 0x2000
	s_add_u32 s24, s12, 0x40000
	s_addc_u32 s25, s13, 0
	s_add_i32 s19, s76, s4
	global_load_lds_dwordx4 v134, s[12:13]
	s_mov_b32 m0, s19
	s_nop 0
	global_load_lds_dwordx4 v130, s[24:25]
	s_add_i32 m0, s19, 0x2000
	s_nop 0
	global_load_lds_dwordx4 v134, s[24:25]
	s_mov_b32 m0, s5
	s_nop 0
	global_load_lds_dwordx4 v128, s[86:87]
	s_mov_b32 m0, s62
	s_nop 0
	global_load_lds_dwordx4 v132, s[86:87]
	s_waitcnt vmcnt(8)
	s_waitcnt lgkmcnt(0)
	s_barrier
	s_setprio 1
	s_waitcnt lgkmcnt(0)
	v_mfma_f32_16x16x32_bf16 v[60:63], v[152:155], v[200:203], v[60:63]
	v_mfma_f32_16x16x32_bf16 v[56:59], v[162:165], v[200:203], v[56:59]
	v_mfma_f32_16x16x32_bf16 v[44:47], v[152:155], v[208:211], v[44:47]
	v_mfma_f32_16x16x32_bf16 v[40:43], v[162:165], v[208:211], v[40:43]
	v_mfma_f32_16x16x32_bf16 v[28:31], v[152:155], v[216:219], v[28:31]
	v_mfma_f32_16x16x32_bf16 v[24:27], v[162:165], v[216:219], v[24:27]
	v_mfma_f32_16x16x32_bf16 v[12:15], v[152:155], v[224:227], v[12:15]
	v_mfma_f32_16x16x32_bf16 v[8:11], v[162:165], v[224:227], v[8:11]
	v_mfma_f32_16x16x32_bf16 v[60:63], v[156:159], v[204:207], v[60:63]
	v_mfma_f32_16x16x32_bf16 v[56:59], v[180:183], v[204:207], v[56:59]
	v_mfma_f32_16x16x32_bf16 v[44:47], v[156:159], v[212:215], v[44:47]
	v_mfma_f32_16x16x32_bf16 v[40:43], v[180:183], v[212:215], v[40:43]
	v_mfma_f32_16x16x32_bf16 v[28:31], v[156:159], v[220:223], v[28:31]
	v_mfma_f32_16x16x32_bf16 v[24:27], v[180:183], v[220:223], v[24:27]
	v_mfma_f32_16x16x32_bf16 v[12:15], v[156:159], v[228:231], v[12:15]
	v_mfma_f32_16x16x32_bf16 v[8:11], v[180:183], v[228:231], v[8:11]
	s_setprio 0
	s_setprio 1
	v_mfma_f32_16x16x32_bf16 v[52:55], v[184:187], v[200:203], v[52:55]
	v_mfma_f32_16x16x32_bf16 v[48:51], v[192:195], v[200:203], v[48:51]
	v_mfma_f32_16x16x32_bf16 v[36:39], v[184:187], v[208:211], v[36:39]
	v_mfma_f32_16x16x32_bf16 v[32:35], v[192:195], v[208:211], v[32:35]
	v_mfma_f32_16x16x32_bf16 v[20:23], v[184:187], v[216:219], v[20:23]
	v_mfma_f32_16x16x32_bf16 v[16:19], v[192:195], v[216:219], v[16:19]
	v_mfma_f32_16x16x32_bf16 v[4:7], v[184:187], v[224:227], v[4:7]
	v_mfma_f32_16x16x32_bf16 v[0:3], v[192:195], v[224:227], v[0:3]
	v_mfma_f32_16x16x32_bf16 v[52:55], v[188:191], v[204:207], v[52:55]
	v_mfma_f32_16x16x32_bf16 v[48:51], v[196:199], v[204:207], v[48:51]
	v_mfma_f32_16x16x32_bf16 v[36:39], v[188:191], v[212:215], v[36:39]
	v_mfma_f32_16x16x32_bf16 v[32:35], v[196:199], v[212:215], v[32:35]
	v_mfma_f32_16x16x32_bf16 v[20:23], v[188:191], v[220:223], v[20:23]
	v_mfma_f32_16x16x32_bf16 v[16:19], v[196:199], v[220:223], v[16:19]
	v_mfma_f32_16x16x32_bf16 v[4:7], v[188:191], v[228:231], v[4:7]
	v_mfma_f32_16x16x32_bf16 v[0:3], v[196:199], v[228:231], v[0:3]
	s_setprio 0
	s_barrier
; #define PG8_STAGE(bufoff, gbase, voff) do { _Pragma("unroll") for (int _i = 0; _i < 2; ++_i) \
;         __builtin_amdgcn_global_load_lds((const unsigned*)((const char*)(gbase) + (voff)[_i]), (LAS unsigned*)(lds + (bufoff) + ldsw + _i * 8192), 16, 0, 0); } while (0)
; #define PG8_LDA(dst, b, h) do { _Pragma("unroll") for (int m = 0; m < 4; ++m) _Pragma("unroll") for (int k = 0; k < 2; ++k) dst[m][k] = *(const LAS bf16x8*)(lds + PG8_SA(b, h) + aoff + m * 2048 + k * 1024); } while (0)
; #define PG8_LDB(dst, b, h) do { _Pragma("unroll") for (int n = 0; n < 2; ++n) _Pragma("unroll") for (int k = 0; k < 2; ++k) dst[n][k] = *(const LAS bf16x8*)(lds + PG8_SB(b, h) + boff + n * 2048 + k * 1024); } while (0)
; #define PG8_MMA(ai, bj, At, Bt) do { __builtin_amdgcn_s_setprio(1); _Pragma("unroll") for (int m = 0; m < 4; ++m) _Pragma("unroll") for (int n = 0; n < 2; ++n) _Pragma("unroll") for (int k = 0; k < 2; ++k) \
;         acc[ai][bj][m][n] = __builtin_amdgcn_mfma_f32_16x16x32_bf16(Bt[n][k], At[m][k], acc[ai][bj][m][n], 0, 0, 0); __builtin_amdgcn_s_setprio(0); } while (0)
; #define PG8_WAIT_V(n) asm volatile("s_waitcnt vmcnt(" #n ")" ::: "memory")
; #define PG8_WAIT_L(n) asm volatile("s_waitcnt lgkmcnt(" #n ")" ::: "memory")
; #define PG8_BAR __builtin_amdgcn_s_barrier()
; #define PG8_SCHED __builtin_amdgcn_sched_barrier(0)
; template <class Epi>
; __device__ __forceinline__ void gemm_phase(LAS unsigned char* lds, const Gemm g, const StaticOrder& S, const Epi& E) {
;     ...
;             PG8_LDB(B0, 1, 0); PG8_LDB(B1, 1, 1); PG8_SCHED; PG8_LDA(At, 1, 0); PG8_STAGE(PG8_SA(0, 1), a2 + hsA, voffA);
;             PG8_WAIT_V(8); PG8_WAIT_L(0); PG8_BAR; PG8_MMA(0, 0, At, B0); PG8_MMA(0, 1, At, B1); PG8_BAR; PG8_SCHED;
;             PG8_LDA(At, 1, 1); PG8_STAGE(PG8_SB(1, 0), b3, voffB); PG8_STAGE(PG8_SB(1, 1), b3 + hsB, voffB); PG8_STAGE(PG8_SA(1, 0), a3, voffA);
;             PG8_WAIT_V(8); PG8_WAIT_L(0); PG8_BAR; PG8_MMA(1, 0, At, B0); PG8_MMA(1, 1, At, B1); PG8_BAR; PG8_SCHED;
;         }
	s_add_i32 s19, 0, 0x18000
	v_add_u32_e32 v136, s19, v166
	s_add_i32 s22, 0, 0x1c000
	ds_read_b128 v[152:155], v136
	ds_read_b128 v[156:159], v136 offset:1024
	ds_read_b128 v[162:165], v136 offset:2048
	ds_read_b128 v[180:183], v136 offset:3072
	v_add_u32_e32 v136, s22, v166
	ds_read_b128 v[184:187], v136
	ds_read_b128 v[188:191], v136 offset:1024
	ds_read_b128 v[192:195], v136 offset:2048
	ds_read_b128 v[196:199], v136 offset:3072
	s_add_u32 s24, s86, 0x40000
	s_addc_u32 s25, s87, 0
	s_mov_b32 m0, s63
	ds_read_b128 v[200:203], v169 offset:32768
	ds_read_b128 v[204:207], v169 offset:33792
	ds_read_b128 v[208:211], v169 offset:34816
	ds_read_b128 v[212:215], v169 offset:35840
	ds_read_b128 v[216:219], v169 offset:36864
	ds_read_b128 v[220:223], v169 offset:37888
	ds_read_b128 v[224:227], v169 offset:38912
	ds_read_b128 v[228:231], v169 offset:39936
	global_load_lds_dwordx4 v128, s[24:25]
	s_mov_b32 m0, s74
	s_nop 0
	global_load_lds_dwordx4 v132, s[24:25]
	s_waitcnt vmcnt(8)
	s_waitcnt lgkmcnt(0)
	s_barrier
	s_setprio 1
	s_waitcnt lgkmcnt(0)
	v_mfma_f32_16x16x32_bf16 v[124:127], v[152:155], v[200:203], v[124:127]
	v_mfma_f32_16x16x32_bf16 v[120:123], v[162:165], v[200:203], v[120:123]
	v_mfma_f32_16x16x32_bf16 v[108:111], v[152:155], v[208:211], v[108:111]
	v_mfma_f32_16x16x32_bf16 v[104:107], v[162:165], v[208:211], v[104:107]
	v_mfma_f32_16x16x32_bf16 v[92:95], v[152:155], v[216:219], v[92:95]
	v_mfma_f32_16x16x32_bf16 v[88:91], v[162:165], v[216:219], v[88:91]
	v_mfma_f32_16x16x32_bf16 v[76:79], v[152:155], v[224:227], v[76:79]
	v_mfma_f32_16x16x32_bf16 v[72:75], v[162:165], v[224:227], v[72:75]
	v_mfma_f32_16x16x32_bf16 v[124:127], v[156:159], v[204:207], v[124:127]
	v_mfma_f32_16x16x32_bf16 v[120:123], v[180:183], v[204:207], v[120:123]
	v_mfma_f32_16x16x32_bf16 v[108:111], v[156:159], v[212:215], v[108:111]
	v_mfma_f32_16x16x32_bf16 v[104:107], v[180:183], v[212:215], v[104:107]
	v_mfma_f32_16x16x32_bf16 v[92:95], v[156:159], v[220:223], v[92:95]
	v_mfma_f32_16x16x32_bf16 v[88:91], v[180:183], v[220:223], v[88:91]
	v_mfma_f32_16x16x32_bf16 v[76:79], v[156:159], v[228:231], v[76:79]
	v_mfma_f32_16x16x32_bf16 v[72:75], v[180:183], v[228:231], v[72:75]
	s_setprio 0
	s_setprio 1
	v_mfma_f32_16x16x32_bf16 v[116:119], v[184:187], v[200:203], v[116:119]
	v_mfma_f32_16x16x32_bf16 v[112:115], v[192:195], v[200:203], v[112:115]
	v_mfma_f32_16x16x32_bf16 v[100:103], v[184:187], v[208:211], v[100:103]
	v_mfma_f32_16x16x32_bf16 v[96:99], v[192:195], v[208:211], v[96:99]
	v_mfma_f32_16x16x32_bf16 v[84:87], v[184:187], v[216:219], v[84:87]
	v_mfma_f32_16x16x32_bf16 v[80:83], v[192:195], v[216:219], v[80:83]
	v_mfma_f32_16x16x32_bf16 v[68:71], v[184:187], v[224:227], v[68:71]
	v_mfma_f32_16x16x32_bf16 v[64:67], v[192:195], v[224:227], v[64:67]
	v_mfma_f32_16x16x32_bf16 v[116:119], v[188:191], v[204:207], v[116:119]
	v_mfma_f32_16x16x32_bf16 v[112:115], v[196:199], v[204:207], v[112:115]
	v_mfma_f32_16x16x32_bf16 v[100:103], v[188:191], v[212:215], v[100:103]
	v_mfma_f32_16x16x32_bf16 v[96:99], v[196:199], v[212:215], v[96:99]
	v_mfma_f32_16x16x32_bf16 v[84:87], v[188:191], v[220:223], v[84:87]
	v_mfma_f32_16x16x32_bf16 v[80:83], v[196:199], v[220:223], v[80:83]
	v_mfma_f32_16x16x32_bf16 v[68:71], v[188:191], v[228:231], v[68:71]
	v_mfma_f32_16x16x32_bf16 v[64:67], v[196:199], v[228:231], v[64:67]
	s_setprio 0
	s_barrier
	s_add_u32 s98, s12, 0x80
	s_addc_u32 s99, s13, 0
	s_add_u32 s100, s86, 0x80
	s_addc_u32 s101, s87, 0
	s_add_i32 s19, s19, s4
	s_mov_b32 m0, s19
	ds_read_b128 v[200:203], v169 offset:49152
	ds_read_b128 v[204:207], v169 offset:50176
	ds_read_b128 v[208:211], v169 offset:51200
	ds_read_b128 v[212:215], v169 offset:52224
	ds_read_b128 v[216:219], v169 offset:53248
	ds_read_b128 v[220:223], v169 offset:54272
	ds_read_b128 v[224:227], v169 offset:55296
	ds_read_b128 v[228:231], v169 offset:56320
	global_load_lds_dwordx4 v130, s[98:99]
	s_add_i32 m0, s19, 0x2000
	s_add_u32 s12, s12, 0x40080
	s_addc_u32 s13, s13, 0
	s_add_i32 s19, s22, s4
	global_load_lds_dwordx4 v134, s[98:99]
	s_mov_b32 m0, s19
	s_nop 0
	global_load_lds_dwordx4 v130, s[12:13]
	s_add_i32 m0, s19, 0x2000
	s_nop 0
	global_load_lds_dwordx4 v134, s[12:13]
	s_mov_b32 m0, s16
	s_nop 0
	global_load_lds_dwordx4 v128, s[100:101]
	s_mov_b32 m0, s33
	s_nop 0
	global_load_lds_dwordx4 v132, s[100:101]
	s_waitcnt vmcnt(8)
	s_waitcnt lgkmcnt(0)
	s_barrier
	s_setprio 1
	s_waitcnt lgkmcnt(0)
	v_mfma_f32_16x16x32_bf16 v[60:63], v[152:155], v[200:203], v[60:63]
	v_mfma_f32_16x16x32_bf16 v[56:59], v[162:165], v[200:203], v[56:59]
	v_mfma_f32_16x16x32_bf16 v[44:47], v[152:155], v[208:211], v[44:47]
	v_mfma_f32_16x16x32_bf16 v[40:43], v[162:165], v[208:211], v[40:43]
	v_mfma_f32_16x16x32_bf16 v[28:31], v[152:155], v[216:219], v[28:31]
	v_mfma_f32_16x16x32_bf16 v[24:27], v[162:165], v[216:219], v[24:27]
	v_mfma_f32_16x16x32_bf16 v[12:15], v[152:155], v[224:227], v[12:15]
	v_mfma_f32_16x16x32_bf16 v[8:11], v[162:165], v[224:227], v[8:11]
	v_mfma_f32_16x16x32_bf16 v[60:63], v[156:159], v[204:207], v[60:63]
	v_mfma_f32_16x16x32_bf16 v[56:59], v[180:183], v[204:207], v[56:59]
	v_mfma_f32_16x16x32_bf16 v[44:47], v[156:159], v[212:215], v[44:47]
	v_mfma_f32_16x16x32_bf16 v[40:43], v[180:183], v[212:215], v[40:43]
	v_mfma_f32_16x16x32_bf16 v[28:31], v[156:159], v[220:223], v[28:31]
	v_mfma_f32_16x16x32_bf16 v[24:27], v[180:183], v[220:223], v[24:27]
	v_mfma_f32_16x16x32_bf16 v[12:15], v[156:159], v[228:231], v[12:15]
	v_mfma_f32_16x16x32_bf16 v[8:11], v[180:183], v[228:231], v[8:11]
	s_setprio 0
	s_setprio 1
	v_mfma_f32_16x16x32_bf16 v[52:55], v[184:187], v[200:203], v[52:55]
	v_mfma_f32_16x16x32_bf16 v[48:51], v[192:195], v[200:203], v[48:51]
	v_mfma_f32_16x16x32_bf16 v[36:39], v[184:187], v[208:211], v[36:39]
	v_mfma_f32_16x16x32_bf16 v[32:35], v[192:195], v[208:211], v[32:35]
	v_mfma_f32_16x16x32_bf16 v[20:23], v[184:187], v[216:219], v[20:23]
	v_mfma_f32_16x16x32_bf16 v[16:19], v[192:195], v[216:219], v[16:19]
	v_mfma_f32_16x16x32_bf16 v[4:7], v[184:187], v[224:227], v[4:7]
	v_mfma_f32_16x16x32_bf16 v[0:3], v[192:195], v[224:227], v[0:3]
	v_mfma_f32_16x16x32_bf16 v[52:55], v[188:191], v[204:207], v[52:55]
	v_mfma_f32_16x16x32_bf16 v[48:51], v[196:199], v[204:207], v[48:51]
	v_mfma_f32_16x16x32_bf16 v[36:39], v[188:191], v[212:215], v[36:39]
	v_mfma_f32_16x16x32_bf16 v[32:35], v[196:199], v[212:215], v[32:35]
	v_mfma_f32_16x16x32_bf16 v[20:23], v[188:191], v[220:223], v[20:23]
	v_mfma_f32_16x16x32_bf16 v[16:19], v[196:199], v[220:223], v[16:19]
	v_mfma_f32_16x16x32_bf16 v[4:7], v[188:191], v[228:231], v[4:7]
	v_mfma_f32_16x16x32_bf16 v[0:3], v[196:199], v[228:231], v[0:3]
	s_setprio 0
	s_barrier
	s_add_i32 s17, s17, 2
	s_add_u32 s10, s10, 0x100
	s_addc_u32 s11, s11, 0
	s_add_u32 s7, s7, 0x100
	s_addc_u32 s15, s15, 0
	s_cmp_gt_u32 s17, 13
	s_cbranch_scc0 .LBB0_414
	s_and_b64 vcc, exec, s[58:59]
	s_cbranch_vccz .LBB0_417
	s_barrier

; #define PG8_STAGE(bufoff, gbase, voff) do { _Pragma("unroll") for (int _i = 0; _i < 2; ++_i) \
;         __builtin_amdgcn_global_load_lds((const unsigned*)((const char*)(gbase) + (voff)[_i]), (LAS unsigned*)(lds + (bufoff) + ldsw + _i * 8192), 16, 0, 0); } while (0)
; #define PG8_LDA(dst, b, h) do { _Pragma("unroll") for (int m = 0; m < 4; ++m) _Pragma("unroll") for (int k = 0; k < 2; ++k) dst[m][k] = *(const LAS bf16x8*)(lds + PG8_SA(b, h) + aoff + m * 2048 + k * 1024); } while (0)
; #define PG8_LDB(dst, b, h) do { _Pragma("unroll") for (int n = 0; n < 2; ++n) _Pragma("unroll") for (int k = 0; k < 2; ++k) dst[n][k] = *(const LAS bf16x8*)(lds + PG8_SB(b, h) + boff + n * 2048 + k * 1024); } while (0)
; #define PG8_MMA(ai, bj, At, Bt) do { __builtin_amdgcn_s_setprio(1); _Pragma("unroll") for (int m = 0; m < 4; ++m) _Pragma("unroll") for (int n = 0; n < 2; ++n) _Pragma("unroll") for (int k = 0; k < 2; ++k) \
;         acc[ai][bj][m][n] = __builtin_amdgcn_mfma_f32_16x16x32_bf16(Bt[n][k], At[m][k], acc[ai][bj][m][n], 0, 0, 0); __builtin_amdgcn_s_setprio(0); } while (0)
; #define PG8_WAIT_V(n) asm volatile("s_waitcnt vmcnt(" #n ")" ::: "memory")
; template <class Epi>
; __device__ __forceinline__ void gemm_phase(LAS unsigned char* lds, const Gemm g, const StaticOrder& S, const Epi& E) {
;     ...
;         for (int t = 0; t < nt; t += 2) {
;             const bool last = (t == nt - 2);
;             if constexpr (Epi::HAS_MID) { if (t == nt1) E.mid(acc, cur, wr, wc, fr, fq); }
;             const char* a1 = cA + ((Epi::HAS_MID && t >= nt1) ? dA2 : 0) + (size_t)(t + 1) * kstep;
;             const char* a2 = last ? nA : cA + ((Epi::HAS_MID && t + 2 >= nt1) ? dA2 : 0) + (size_t)(t + 2) * kstep; const char* b2 = last ? nB : cB + ((Epi::HAS_MID && t + 2 >= nt1) ? dB2 : 0) + (size_t)(t + 2) * kstep;
;             const char* a3 = a2 + kstep; const char* b3 = b2 + kstep;
;             PG8_LDB(B0, 0, 0); PG8_LDB(B1, 0, 1); PG8_SCHED; PG8_LDA(At, 0, 0); PG8_STAGE(PG8_SA(1, 1), a1 + hsA, voffA);
;             PG8_WAIT_V(8); PG8_WAIT_L(0); PG8_BAR; PG8_MMA(0, 0, At, B0); PG8_MMA(0, 1, At, B1); PG8_BAR; PG8_SCHED;
;             PG8_LDA(At, 0, 1); PG8_STAGE(PG8_SB(0, 0), b2, voffB); PG8_STAGE(PG8_SB(0, 1), b2 + hsB, voffB); PG8_STAGE(PG8_SA(0, 0), a2, voffA);
;             PG8_WAIT_V(8); PG8_WAIT_L(0); PG8_BAR; PG8_MMA(1, 0, At, B0); PG8_MMA(1, 1, At, B1); PG8_BAR; PG8_SCHED;
.LBB0_720:
	ds_read_b128 v[128:131], v182
	ds_read_b128 v[132:135], v182 offset:1024
	ds_read_b128 v[136:139], v182 offset:2048
	ds_read_b128 v[140:143], v182 offset:3072
	ds_read_b128 v[166:169], v183
	ds_read_b128 v[188:191], v183 offset:1024
	ds_read_b128 v[192:195], v183 offset:2048
	ds_read_b128 v[196:199], v183 offset:3072
	s_add_u32 s39, s62, 0xfffc0080
	s_addc_u32 s40, s63, -1
	s_cmp_eq_u32 s38, 12
	s_cselect_b32 s67, s6, s40
	s_cselect_b32 s66, s7, s39
	s_cselect_b32 s65, s15, s37
	s_cselect_b32 s64, s35, s36
	s_add_i32 m0, s4, 0xc000
	ds_read_b128 v[200:203], v184
	ds_read_b128 v[204:207], v184 offset:1024
	ds_read_b128 v[208:211], v184 offset:2048
	ds_read_b128 v[212:215], v184 offset:3072
	ds_read_b128 v[216:219], v184 offset:4096
	ds_read_b128 v[220:223], v184 offset:5120
	ds_read_b128 v[224:227], v184 offset:6144
	ds_read_b128 v[228:231], v184 offset:7168
	global_load_lds_dwordx4 v156, s[62:63]
	s_add_i32 m0, s4, 0xe000
	s_nop 0
	global_load_lds_dwordx4 v158, s[62:63]
	s_waitcnt vmcnt(8)
	s_waitcnt lgkmcnt(0)
	s_barrier
	s_setprio 1
	s_waitcnt lgkmcnt(0)
	v_mfma_f32_16x16x32_bf16 v[124:127], v[128:131], v[200:203], v[124:127]
	v_mfma_f32_16x16x32_bf16 v[120:123], v[136:139], v[200:203], v[120:123]
	v_mfma_f32_16x16x32_bf16 v[108:111], v[128:131], v[208:211], v[108:111]
	v_mfma_f32_16x16x32_bf16 v[104:107], v[136:139], v[208:211], v[104:107]
	v_mfma_f32_16x16x32_bf16 v[92:95], v[128:131], v[216:219], v[92:95]
	v_mfma_f32_16x16x32_bf16 v[88:91], v[136:139], v[216:219], v[88:91]
	v_mfma_f32_16x16x32_bf16 v[76:79], v[128:131], v[224:227], v[76:79]
	v_mfma_f32_16x16x32_bf16 v[72:75], v[136:139], v[224:227], v[72:75]
	v_mfma_f32_16x16x32_bf16 v[124:127], v[132:135], v[204:207], v[124:127]
	v_mfma_f32_16x16x32_bf16 v[120:123], v[140:143], v[204:207], v[120:123]
	v_mfma_f32_16x16x32_bf16 v[108:111], v[132:135], v[212:215], v[108:111]
	v_mfma_f32_16x16x32_bf16 v[104:107], v[140:143], v[212:215], v[104:107]
	v_mfma_f32_16x16x32_bf16 v[92:95], v[132:135], v[220:223], v[92:95]
	v_mfma_f32_16x16x32_bf16 v[88:91], v[140:143], v[220:223], v[88:91]
	v_mfma_f32_16x16x32_bf16 v[76:79], v[132:135], v[228:231], v[76:79]
	v_mfma_f32_16x16x32_bf16 v[72:75], v[140:143], v[228:231], v[72:75]
	s_setprio 0
	s_setprio 1
	v_mfma_f32_16x16x32_bf16 v[116:119], v[166:169], v[200:203], v[116:119]
	v_mfma_f32_16x16x32_bf16 v[112:115], v[192:195], v[200:203], v[112:115]
	v_mfma_f32_16x16x32_bf16 v[100:103], v[166:169], v[208:211], v[100:103]
	v_mfma_f32_16x16x32_bf16 v[96:99], v[192:195], v[208:211], v[96:99]
	v_mfma_f32_16x16x32_bf16 v[84:87], v[166:169], v[216:219], v[84:87]
	v_mfma_f32_16x16x32_bf16 v[80:83], v[192:195], v[216:219], v[80:83]
	v_mfma_f32_16x16x32_bf16 v[68:71], v[166:169], v[224:227], v[68:71]
	v_mfma_f32_16x16x32_bf16 v[64:67], v[192:195], v[224:227], v[64:67]
	v_mfma_f32_16x16x32_bf16 v[116:119], v[188:191], v[204:207], v[116:119]
	v_mfma_f32_16x16x32_bf16 v[112:115], v[196:199], v[204:207], v[112:115]
	v_mfma_f32_16x16x32_bf16 v[100:103], v[188:191], v[212:215], v[100:103]
	v_mfma_f32_16x16x32_bf16 v[96:99], v[196:199], v[212:215], v[96:99]
	v_mfma_f32_16x16x32_bf16 v[84:87], v[188:191], v[220:223], v[84:87]
	v_mfma_f32_16x16x32_bf16 v[80:83], v[196:199], v[220:223], v[80:83]
	v_mfma_f32_16x16x32_bf16 v[68:71], v[188:191], v[228:231], v[68:71]
	v_mfma_f32_16x16x32_bf16 v[64:67], v[196:199], v[228:231], v[64:67]
	s_setprio 0
	s_barrier
	s_add_i32 s39, s27, s3
	s_mov_b32 m0, s39
	ds_read_b128 v[200:203], v184 offset:16384
	ds_read_b128 v[204:207], v184 offset:17408
	ds_read_b128 v[208:211], v184 offset:18432
	ds_read_b128 v[212:215], v184 offset:19456
	ds_read_b128 v[216:219], v184 offset:20480
	ds_read_b128 v[220:223], v184 offset:21504
	ds_read_b128 v[224:227], v184 offset:22528
	ds_read_b128 v[228:231], v184 offset:23552
	global_load_lds_dwordx4 v146, s[64:65]
	s_add_i32 m0, s39, 0x2000
	s_add_u32 s40, s64, 0x40000
	s_addc_u32 s41, s65, 0
	s_add_i32 s39, s28, s3
	global_load_lds_dwordx4 v150, s[64:65]
	s_mov_b32 m0, s39
	s_nop 0
	global_load_lds_dwordx4 v146, s[40:41]
	s_add_i32 m0, s39, 0x2000
	s_nop 0
	global_load_lds_dwordx4 v150, s[40:41]
	s_mov_b32 m0, s4
	s_nop 0
	global_load_lds_dwordx4 v144, s[66:67]
	s_mov_b32 m0, s5
	s_nop 0
	global_load_lds_dwordx4 v148, s[66:67]
	s_waitcnt vmcnt(8)
	s_waitcnt lgkmcnt(0)
	s_barrier
	s_setprio 1
	s_waitcnt lgkmcnt(0)
	v_mfma_f32_16x16x32_bf16 v[60:63], v[128:131], v[200:203], v[60:63]
	v_mfma_f32_16x16x32_bf16 v[56:59], v[136:139], v[200:203], v[56:59]
	v_mfma_f32_16x16x32_bf16 v[44:47], v[128:131], v[208:211], v[44:47]
	v_mfma_f32_16x16x32_bf16 v[40:43], v[136:139], v[208:211], v[40:43]
	v_mfma_f32_16x16x32_bf16 v[28:31], v[128:131], v[216:219], v[28:31]
	v_mfma_f32_16x16x32_bf16 v[24:27], v[136:139], v[216:219], v[24:27]
	v_mfma_f32_16x16x32_bf16 v[12:15], v[128:131], v[224:227], v[12:15]
	v_mfma_f32_16x16x32_bf16 v[8:11], v[136:139], v[224:227], v[8:11]
	v_mfma_f32_16x16x32_bf16 v[60:63], v[132:135], v[204:207], v[60:63]
	v_mfma_f32_16x16x32_bf16 v[56:59], v[140:143], v[204:207], v[56:59]
	v_mfma_f32_16x16x32_bf16 v[44:47], v[132:135], v[212:215], v[44:47]
	v_mfma_f32_16x16x32_bf16 v[40:43], v[140:143], v[212:215], v[40:43]
	v_mfma_f32_16x16x32_bf16 v[28:31], v[132:135], v[220:223], v[28:31]
	v_mfma_f32_16x16x32_bf16 v[24:27], v[140:143], v[220:223], v[24:27]
	v_mfma_f32_16x16x32_bf16 v[12:15], v[132:135], v[228:231], v[12:15]
	v_mfma_f32_16x16x32_bf16 v[8:11], v[140:143], v[228:231], v[8:11]
	s_setprio 0
	s_setprio 1
	v_mfma_f32_16x16x32_bf16 v[52:55], v[166:169], v[200:203], v[52:55]
	v_mfma_f32_16x16x32_bf16 v[48:51], v[192:195], v[200:203], v[48:51]
	v_mfma_f32_16x16x32_bf16 v[36:39], v[166:169], v[208:211], v[36:39]
	v_mfma_f32_16x16x32_bf16 v[32:35], v[192:195], v[208:211], v[32:35]
	v_mfma_f32_16x16x32_bf16 v[20:23], v[166:169], v[216:219], v[20:23]
	v_mfma_f32_16x16x32_bf16 v[16:19], v[192:195], v[216:219], v[16:19]
	v_mfma_f32_16x16x32_bf16 v[4:7], v[166:169], v[224:227], v[4:7]
	v_mfma_f32_16x16x32_bf16 v[0:3], v[192:195], v[224:227], v[0:3]
	v_mfma_f32_16x16x32_bf16 v[52:55], v[188:191], v[204:207], v[52:55]
	v_mfma_f32_16x16x32_bf16 v[48:51], v[196:199], v[204:207], v[48:51]
	v_mfma_f32_16x16x32_bf16 v[36:39], v[188:191], v[212:215], v[36:39]
	v_mfma_f32_16x16x32_bf16 v[32:35], v[196:199], v[212:215], v[32:35]
	v_mfma_f32_16x16x32_bf16 v[20:23], v[188:191], v[220:223], v[20:23]
	v_mfma_f32_16x16x32_bf16 v[16:19], v[196:199], v[220:223], v[16:19]
	v_mfma_f32_16x16x32_bf16 v[4:7], v[188:191], v[228:231], v[4:7]
	v_mfma_f32_16x16x32_bf16 v[0:3], v[196:199], v[228:231], v[0:3]
	s_setprio 0
	s_barrier
; #define PG8_STAGE(bufoff, gbase, voff) do { _Pragma("unroll") for (int _i = 0; _i < 2; ++_i) \
;         __builtin_amdgcn_global_load_lds((const unsigned*)((const char*)(gbase) + (voff)[_i]), (LAS unsigned*)(lds + (bufoff) + ldsw + _i * 8192), 16, 0, 0); } while (0)
; #define PG8_LDA(dst, b, h) do { _Pragma("unroll") for (int m = 0; m < 4; ++m) _Pragma("unroll") for (int k = 0; k < 2; ++k) dst[m][k] = *(const LAS bf16x8*)(lds + PG8_SA(b, h) + aoff + m * 2048 + k * 1024); } while (0)
; #define PG8_LDB(dst, b, h) do { _Pragma("unroll") for (int n = 0; n < 2; ++n) _Pragma("unroll") for (int k = 0; k < 2; ++k) dst[n][k] = *(const LAS bf16x8*)(lds + PG8_SB(b, h) + boff + n * 2048 + k * 1024); } while (0)
; #define PG8_MMA(ai, bj, At, Bt) do { __builtin_amdgcn_s_setprio(1); _Pragma("unroll") for (int m = 0; m < 4; ++m) _Pragma("unroll") for (int n = 0; n < 2; ++n) _Pragma("unroll") for (int k = 0; k < 2; ++k) \
;         acc[ai][bj][m][n] = __builtin_amdgcn_mfma_f32_16x16x32_bf16(Bt[n][k], At[m][k], acc[ai][bj][m][n], 0, 0, 0); __builtin_amdgcn_s_setprio(0); } while (0)
; #define PG8_WAIT_V(n) asm volatile("s_waitcnt vmcnt(" #n ")" ::: "memory")
; #define PG8_WAIT_L(n) asm volatile("s_waitcnt lgkmcnt(" #n ")" ::: "memory")
; #define PG8_BAR __builtin_amdgcn_s_barrier()
; #define PG8_SCHED __builtin_amdgcn_sched_barrier(0)
; template <class Epi>
; __device__ __forceinline__ void gemm_phase(LAS unsigned char* lds, const Gemm g, const StaticOrder& S, const Epi& E) {
;     ...
;             PG8_LDB(B0, 1, 0); PG8_LDB(B1, 1, 1); PG8_SCHED; PG8_LDA(At, 1, 0); PG8_STAGE(PG8_SA(0, 1), a2 + hsA, voffA);
;             PG8_WAIT_V(8); PG8_WAIT_L(0); PG8_BAR; PG8_MMA(0, 0, At, B0); PG8_MMA(0, 1, At, B1); PG8_BAR; PG8_SCHED;
;             PG8_LDA(At, 1, 1); PG8_STAGE(PG8_SB(1, 0), b3, voffB); PG8_STAGE(PG8_SB(1, 1), b3 + hsB, voffB); PG8_STAGE(PG8_SA(1, 0), a3, voffA);
;             PG8_WAIT_V(8); PG8_WAIT_L(0); PG8_BAR; PG8_MMA(1, 0, At, B0); PG8_MMA(1, 1, At, B1); PG8_BAR; PG8_SCHED;
;         }
	s_add_i32 s39, 0, 0x18000
	s_add_i32 s42, 0, 0x1c000
	v_add_u32_e32 v140, s39, v173
	v_add_u32_e32 v152, s42, v173
	ds_read_b128 v[128:131], v140
	ds_read_b128 v[132:135], v140 offset:1024
	ds_read_b128 v[136:139], v140 offset:2048
	ds_read_b128 v[140:143], v140 offset:3072
	ds_read_b128 v[166:169], v152
	ds_read_b128 v[188:191], v152 offset:1024
	ds_read_b128 v[192:195], v152 offset:2048
	ds_read_b128 v[196:199], v152 offset:3072
	s_add_u32 s40, s66, 0x40000
	s_addc_u32 s41, s67, 0
	s_mov_b32 m0, s16
	ds_read_b128 v[200:203], v184 offset:32768
	ds_read_b128 v[204:207], v184 offset:33792
	ds_read_b128 v[208:211], v184 offset:34816
	ds_read_b128 v[212:215], v184 offset:35840
	ds_read_b128 v[216:219], v184 offset:36864
	ds_read_b128 v[220:223], v184 offset:37888
	ds_read_b128 v[224:227], v184 offset:38912
	ds_read_b128 v[228:231], v184 offset:39936
	global_load_lds_dwordx4 v144, s[40:41]
	s_mov_b32 m0, s17
	s_nop 0
	global_load_lds_dwordx4 v148, s[40:41]
	s_waitcnt vmcnt(8)
	s_waitcnt lgkmcnt(0)
	s_barrier
	s_setprio 1
	s_waitcnt lgkmcnt(0)
	v_mfma_f32_16x16x32_bf16 v[124:127], v[128:131], v[200:203], v[124:127]
	v_mfma_f32_16x16x32_bf16 v[120:123], v[136:139], v[200:203], v[120:123]
	v_mfma_f32_16x16x32_bf16 v[108:111], v[128:131], v[208:211], v[108:111]
	v_mfma_f32_16x16x32_bf16 v[104:107], v[136:139], v[208:211], v[104:107]
	v_mfma_f32_16x16x32_bf16 v[92:95], v[128:131], v[216:219], v[92:95]
	v_mfma_f32_16x16x32_bf16 v[88:91], v[136:139], v[216:219], v[88:91]
	v_mfma_f32_16x16x32_bf16 v[76:79], v[128:131], v[224:227], v[76:79]
	v_mfma_f32_16x16x32_bf16 v[72:75], v[136:139], v[224:227], v[72:75]
	v_mfma_f32_16x16x32_bf16 v[124:127], v[132:135], v[204:207], v[124:127]
	v_mfma_f32_16x16x32_bf16 v[120:123], v[140:143], v[204:207], v[120:123]
	v_mfma_f32_16x16x32_bf16 v[108:111], v[132:135], v[212:215], v[108:111]
	v_mfma_f32_16x16x32_bf16 v[104:107], v[140:143], v[212:215], v[104:107]
	v_mfma_f32_16x16x32_bf16 v[92:95], v[132:135], v[220:223], v[92:95]
	v_mfma_f32_16x16x32_bf16 v[88:91], v[140:143], v[220:223], v[88:91]
	v_mfma_f32_16x16x32_bf16 v[76:79], v[132:135], v[228:231], v[76:79]
	v_mfma_f32_16x16x32_bf16 v[72:75], v[140:143], v[228:231], v[72:75]
	s_setprio 0
	s_setprio 1
	v_mfma_f32_16x16x32_bf16 v[116:119], v[166:169], v[200:203], v[116:119]
	v_mfma_f32_16x16x32_bf16 v[112:115], v[192:195], v[200:203], v[112:115]
	v_mfma_f32_16x16x32_bf16 v[100:103], v[166:169], v[208:211], v[100:103]
	v_mfma_f32_16x16x32_bf16 v[96:99], v[192:195], v[208:211], v[96:99]
	v_mfma_f32_16x16x32_bf16 v[84:87], v[166:169], v[216:219], v[84:87]
	v_mfma_f32_16x16x32_bf16 v[80:83], v[192:195], v[216:219], v[80:83]
	v_mfma_f32_16x16x32_bf16 v[68:71], v[166:169], v[224:227], v[68:71]
	v_mfma_f32_16x16x32_bf16 v[64:67], v[192:195], v[224:227], v[64:67]
	v_mfma_f32_16x16x32_bf16 v[116:119], v[188:191], v[204:207], v[116:119]
	v_mfma_f32_16x16x32_bf16 v[112:115], v[196:199], v[204:207], v[112:115]
	v_mfma_f32_16x16x32_bf16 v[100:103], v[188:191], v[212:215], v[100:103]
	v_mfma_f32_16x16x32_bf16 v[96:99], v[196:199], v[212:215], v[96:99]
	v_mfma_f32_16x16x32_bf16 v[84:87], v[188:191], v[220:223], v[84:87]
	v_mfma_f32_16x16x32_bf16 v[80:83], v[196:199], v[220:223], v[80:83]
	v_mfma_f32_16x16x32_bf16 v[68:71], v[188:191], v[228:231], v[68:71]
	v_mfma_f32_16x16x32_bf16 v[64:67], v[196:199], v[228:231], v[64:67]
	s_setprio 0
	s_barrier
	s_add_u32 s98, s64, 0x80
	s_addc_u32 s99, s65, 0
	s_add_u32 s100, s66, 0x80
	s_addc_u32 s101, s67, 0
	s_add_i32 s39, s39, s3
	s_mov_b32 m0, s39
	ds_read_b128 v[200:203], v184 offset:49152
	ds_read_b128 v[204:207], v184 offset:50176
	ds_read_b128 v[208:211], v184 offset:51200
	ds_read_b128 v[212:215], v184 offset:52224
	ds_read_b128 v[216:219], v184 offset:53248
	ds_read_b128 v[220:223], v184 offset:54272
	ds_read_b128 v[224:227], v184 offset:55296
	ds_read_b128 v[228:231], v184 offset:56320
	global_load_lds_dwordx4 v146, s[98:99]
	s_add_i32 m0, s39, 0x2000
	s_add_u32 s40, s64, 0x40080
	s_addc_u32 s41, s65, 0
	s_add_i32 s39, s42, s3
	global_load_lds_dwordx4 v150, s[98:99]
	s_mov_b32 m0, s39
	s_nop 0
	global_load_lds_dwordx4 v146, s[40:41]
	s_add_i32 m0, s39, 0x2000
	s_nop 0
	global_load_lds_dwordx4 v150, s[40:41]
	s_mov_b32 m0, s22
	s_nop 0
	global_load_lds_dwordx4 v144, s[100:101]
	s_mov_b32 m0, s23
	s_nop 0
	global_load_lds_dwordx4 v148, s[100:101]
	s_waitcnt vmcnt(8)
	s_waitcnt lgkmcnt(0)
	s_barrier
	s_setprio 1
	s_waitcnt lgkmcnt(0)
	v_mfma_f32_16x16x32_bf16 v[60:63], v[128:131], v[200:203], v[60:63]
	v_mfma_f32_16x16x32_bf16 v[56:59], v[136:139], v[200:203], v[56:59]
	v_mfma_f32_16x16x32_bf16 v[44:47], v[128:131], v[208:211], v[44:47]
	v_mfma_f32_16x16x32_bf16 v[40:43], v[136:139], v[208:211], v[40:43]
	v_mfma_f32_16x16x32_bf16 v[28:31], v[128:131], v[216:219], v[28:31]
	v_mfma_f32_16x16x32_bf16 v[24:27], v[136:139], v[216:219], v[24:27]
	v_mfma_f32_16x16x32_bf16 v[12:15], v[128:131], v[224:227], v[12:15]
	v_mfma_f32_16x16x32_bf16 v[8:11], v[136:139], v[224:227], v[8:11]
	v_mfma_f32_16x16x32_bf16 v[60:63], v[132:135], v[204:207], v[60:63]
	v_mfma_f32_16x16x32_bf16 v[56:59], v[140:143], v[204:207], v[56:59]
	v_mfma_f32_16x16x32_bf16 v[44:47], v[132:135], v[212:215], v[44:47]
	v_mfma_f32_16x16x32_bf16 v[40:43], v[140:143], v[212:215], v[40:43]
	v_mfma_f32_16x16x32_bf16 v[28:31], v[132:135], v[220:223], v[28:31]
	v_mfma_f32_16x16x32_bf16 v[24:27], v[140:143], v[220:223], v[24:27]
	v_mfma_f32_16x16x32_bf16 v[12:15], v[132:135], v[228:231], v[12:15]
	v_mfma_f32_16x16x32_bf16 v[8:11], v[140:143], v[228:231], v[8:11]
	s_setprio 0
	s_setprio 1
	v_mfma_f32_16x16x32_bf16 v[52:55], v[166:169], v[200:203], v[52:55]
	v_mfma_f32_16x16x32_bf16 v[48:51], v[192:195], v[200:203], v[48:51]
	v_mfma_f32_16x16x32_bf16 v[36:39], v[166:169], v[208:211], v[36:39]
	v_mfma_f32_16x16x32_bf16 v[32:35], v[192:195], v[208:211], v[32:35]
	v_mfma_f32_16x16x32_bf16 v[20:23], v[166:169], v[216:219], v[20:23]
	v_mfma_f32_16x16x32_bf16 v[16:19], v[192:195], v[216:219], v[16:19]
	v_mfma_f32_16x16x32_bf16 v[4:7], v[166:169], v[224:227], v[4:7]
	v_mfma_f32_16x16x32_bf16 v[0:3], v[192:195], v[224:227], v[0:3]
	v_mfma_f32_16x16x32_bf16 v[52:55], v[188:191], v[204:207], v[52:55]
	v_mfma_f32_16x16x32_bf16 v[48:51], v[196:199], v[204:207], v[48:51]
	v_mfma_f32_16x16x32_bf16 v[36:39], v[188:191], v[212:215], v[36:39]
	v_mfma_f32_16x16x32_bf16 v[32:35], v[196:199], v[212:215], v[32:35]
	v_mfma_f32_16x16x32_bf16 v[20:23], v[188:191], v[220:223], v[20:23]
	v_mfma_f32_16x16x32_bf16 v[16:19], v[196:199], v[220:223], v[16:19]
	v_mfma_f32_16x16x32_bf16 v[4:7], v[188:191], v[228:231], v[4:7]
	v_mfma_f32_16x16x32_bf16 v[0:3], v[196:199], v[228:231], v[0:3]
	s_setprio 0
	s_barrier
	s_add_i32 s38, s38, 2
	s_add_u32 s62, s62, 0x100
	s_addc_u32 s63, s63, 0
	s_add_u32 s36, s36, 0x100
	s_addc_u32 s37, s37, 0
	s_cmp_gt_u32 s38, 13
	s_cbranch_scc0 .LBB0_720
	s_and_b64 vcc, exec, s[12:13]
	s_cbranch_vccz .LBB0_723
	s_barrier

; #define PG8_STAGE(bufoff, gbase, voff) do { _Pragma("unroll") for (int _i = 0; _i < 2; ++_i) \
;         __builtin_amdgcn_global_load_lds((const unsigned*)((const char*)(gbase) + (voff)[_i]), (LAS unsigned*)(lds + (bufoff) + ldsw + _i * 8192), 16, 0, 0); } while (0)
; #define PG8_LDA(dst, b, h) do { _Pragma("unroll") for (int m = 0; m < 4; ++m) _Pragma("unroll") for (int k = 0; k < 2; ++k) dst[m][k] = *(const LAS bf16x8*)(lds + PG8_SA(b, h) + aoff + m * 2048 + k * 1024); } while (0)
; #define PG8_LDB(dst, b, h) do { _Pragma("unroll") for (int n = 0; n < 2; ++n) _Pragma("unroll") for (int k = 0; k < 2; ++k) dst[n][k] = *(const LAS bf16x8*)(lds + PG8_SB(b, h) + boff + n * 2048 + k * 1024); } while (0)
; #define PG8_MMA(ai, bj, At, Bt) do { __builtin_amdgcn_s_setprio(1); _Pragma("unroll") for (int m = 0; m < 4; ++m) _Pragma("unroll") for (int n = 0; n < 2; ++n) _Pragma("unroll") for (int k = 0; k < 2; ++k) \
;         acc[ai][bj][m][n] = __builtin_amdgcn_mfma_f32_16x16x32_bf16(Bt[n][k], At[m][k], acc[ai][bj][m][n], 0, 0, 0); __builtin_amdgcn_s_setprio(0); } while (0)
; #define PG8_WAIT_V(n) asm volatile("s_waitcnt vmcnt(" #n ")" ::: "memory")
; template <class Epi>
; __device__ __forceinline__ void gemm_phase(LAS unsigned char* lds, const Gemm g, const StaticOrder& S, const Epi& E) {
;     ...
;         for (int t = 0; t < nt; t += 2) {
;             const bool last = (t == nt - 2);
;             if constexpr (Epi::HAS_MID) { if (t == nt1) E.mid(acc, cur, wr, wc, fr, fq); }
;             const char* a1 = cA + ((Epi::HAS_MID && t >= nt1) ? dA2 : 0) + (size_t)(t + 1) * kstep;
;             const char* a2 = last ? nA : cA + ((Epi::HAS_MID && t + 2 >= nt1) ? dA2 : 0) + (size_t)(t + 2) * kstep; const char* b2 = last ? nB : cB + ((Epi::HAS_MID && t + 2 >= nt1) ? dB2 : 0) + (size_t)(t + 2) * kstep;
;             const char* a3 = a2 + kstep; const char* b3 = b2 + kstep;
;             PG8_LDB(B0, 0, 0); PG8_LDB(B1, 0, 1); PG8_SCHED; PG8_LDA(At, 0, 0); PG8_STAGE(PG8_SA(1, 1), a1 + hsA, voffA);
;             PG8_WAIT_V(8); PG8_WAIT_L(0); PG8_BAR; PG8_MMA(0, 0, At, B0); PG8_MMA(0, 1, At, B1); PG8_BAR; PG8_SCHED;
;             PG8_LDA(At, 0, 1); PG8_STAGE(PG8_SB(0, 0), b2, voffB); PG8_STAGE(PG8_SB(0, 1), b2 + hsB, voffB); PG8_STAGE(PG8_SA(0, 0), a2, voffA);
;             PG8_WAIT_V(8); PG8_WAIT_L(0); PG8_BAR; PG8_MMA(1, 0, At, B0); PG8_MMA(1, 1, At, B1); PG8_BAR; PG8_SCHED;
.LBB0_1234:
	ds_read_b128 v[144:147], v155
	ds_read_b128 v[148:151], v155 offset:1024
	ds_read_b128 v[162:165], v155 offset:2048
	ds_read_b128 v[166:169], v155 offset:3072
	ds_read_b128 v[170:173], v156
	ds_read_b128 v[174:177], v156 offset:1024
	ds_read_b128 v[184:187], v156 offset:2048
	ds_read_b128 v[188:191], v156 offset:3072
	s_add_u32 s39, s48, 0xfffc0080
	s_addc_u32 s41, s49, -1
	s_cmp_eq_u32 s35, 12
	s_cselect_b32 s53, s0, s41
	s_cselect_b32 s52, s1, s39
	s_cselect_b32 s51, s6, s34
	s_cselect_b32 s50, s7, s13
	s_add_i32 m0, s5, 0xc000
	ds_read_b128 v[192:195], v157
	ds_read_b128 v[196:199], v157 offset:1024
	ds_read_b128 v[200:203], v157 offset:2048
	ds_read_b128 v[204:207], v157 offset:3072
	ds_read_b128 v[208:211], v157 offset:4096
	ds_read_b128 v[212:215], v157 offset:5120
	ds_read_b128 v[216:219], v157 offset:6144
	ds_read_b128 v[220:223], v157 offset:7168
	global_load_lds_dwordx4 v136, s[48:49]
	s_add_i32 m0, s5, 0xe000
	s_nop 0
	global_load_lds_dwordx4 v138, s[48:49]
	s_waitcnt vmcnt(8)
	s_waitcnt lgkmcnt(0)
	s_barrier
	s_setprio 1
	s_waitcnt lgkmcnt(0)
	v_mfma_f32_16x16x32_bf16 v[124:127], v[144:147], v[192:195], v[124:127]
	v_mfma_f32_16x16x32_bf16 v[120:123], v[162:165], v[192:195], v[120:123]
	v_mfma_f32_16x16x32_bf16 v[108:111], v[144:147], v[200:203], v[108:111]
	v_mfma_f32_16x16x32_bf16 v[104:107], v[162:165], v[200:203], v[104:107]
	v_mfma_f32_16x16x32_bf16 v[92:95], v[144:147], v[208:211], v[92:95]
	v_mfma_f32_16x16x32_bf16 v[88:91], v[162:165], v[208:211], v[88:91]
	v_mfma_f32_16x16x32_bf16 v[76:79], v[144:147], v[216:219], v[76:79]
	v_mfma_f32_16x16x32_bf16 v[72:75], v[162:165], v[216:219], v[72:75]
	v_mfma_f32_16x16x32_bf16 v[124:127], v[148:151], v[196:199], v[124:127]
	v_mfma_f32_16x16x32_bf16 v[120:123], v[166:169], v[196:199], v[120:123]
	v_mfma_f32_16x16x32_bf16 v[108:111], v[148:151], v[204:207], v[108:111]
	v_mfma_f32_16x16x32_bf16 v[104:107], v[166:169], v[204:207], v[104:107]
	v_mfma_f32_16x16x32_bf16 v[92:95], v[148:151], v[212:215], v[92:95]
	v_mfma_f32_16x16x32_bf16 v[88:91], v[166:169], v[212:215], v[88:91]
	v_mfma_f32_16x16x32_bf16 v[76:79], v[148:151], v[220:223], v[76:79]
	v_mfma_f32_16x16x32_bf16 v[72:75], v[166:169], v[220:223], v[72:75]
	s_setprio 0
	s_setprio 1
	v_mfma_f32_16x16x32_bf16 v[116:119], v[170:173], v[192:195], v[116:119]
	v_mfma_f32_16x16x32_bf16 v[112:115], v[184:187], v[192:195], v[112:115]
	v_mfma_f32_16x16x32_bf16 v[100:103], v[170:173], v[200:203], v[100:103]
	v_mfma_f32_16x16x32_bf16 v[96:99], v[184:187], v[200:203], v[96:99]
	v_mfma_f32_16x16x32_bf16 v[84:87], v[170:173], v[208:211], v[84:87]
	v_mfma_f32_16x16x32_bf16 v[80:83], v[184:187], v[208:211], v[80:83]
	v_mfma_f32_16x16x32_bf16 v[68:71], v[170:173], v[216:219], v[68:71]
	v_mfma_f32_16x16x32_bf16 v[64:67], v[184:187], v[216:219], v[64:67]
	v_mfma_f32_16x16x32_bf16 v[116:119], v[174:177], v[196:199], v[116:119]
	v_mfma_f32_16x16x32_bf16 v[112:115], v[188:191], v[196:199], v[112:115]
	v_mfma_f32_16x16x32_bf16 v[100:103], v[174:177], v[204:207], v[100:103]
	v_mfma_f32_16x16x32_bf16 v[96:99], v[188:191], v[204:207], v[96:99]
	v_mfma_f32_16x16x32_bf16 v[84:87], v[174:177], v[212:215], v[84:87]
	v_mfma_f32_16x16x32_bf16 v[80:83], v[188:191], v[212:215], v[80:83]
	v_mfma_f32_16x16x32_bf16 v[68:71], v[174:177], v[220:223], v[68:71]
	v_mfma_f32_16x16x32_bf16 v[64:67], v[188:191], v[220:223], v[64:67]
	s_setprio 0
	s_barrier
	s_add_i32 s39, s31, s4
	s_mov_b32 m0, s39
	ds_read_b128 v[192:195], v157 offset:16384
	ds_read_b128 v[196:199], v157 offset:17408
	ds_read_b128 v[200:203], v157 offset:18432
	ds_read_b128 v[204:207], v157 offset:19456
	ds_read_b128 v[208:211], v157 offset:20480
	ds_read_b128 v[212:215], v157 offset:21504
	ds_read_b128 v[216:219], v157 offset:22528
	ds_read_b128 v[220:223], v157 offset:23552
	global_load_lds_dwordx4 v130, s[50:51]
	s_add_i32 m0, s39, 0x2000
	s_add_u32 s54, s50, 0x40000
	s_addc_u32 s55, s51, 0
	s_add_i32 s39, s33, s4
	global_load_lds_dwordx4 v134, s[50:51]
	s_mov_b32 m0, s39
	s_nop 0
	global_load_lds_dwordx4 v130, s[54:55]
	s_add_i32 m0, s39, 0x2000
	s_nop 0
	global_load_lds_dwordx4 v134, s[54:55]
	s_mov_b32 m0, s5
	s_nop 0
	global_load_lds_dwordx4 v128, s[52:53]
	s_mov_b32 m0, s16
	s_nop 0
	global_load_lds_dwordx4 v132, s[52:53]
	s_waitcnt vmcnt(8)
	s_waitcnt lgkmcnt(0)
	s_barrier
	s_setprio 1
	s_waitcnt lgkmcnt(0)
	v_mfma_f32_16x16x32_bf16 v[60:63], v[144:147], v[192:195], v[60:63]
	v_mfma_f32_16x16x32_bf16 v[56:59], v[162:165], v[192:195], v[56:59]
	v_mfma_f32_16x16x32_bf16 v[44:47], v[144:147], v[200:203], v[44:47]
	v_mfma_f32_16x16x32_bf16 v[40:43], v[162:165], v[200:203], v[40:43]
	v_mfma_f32_16x16x32_bf16 v[28:31], v[144:147], v[208:211], v[28:31]
	v_mfma_f32_16x16x32_bf16 v[24:27], v[162:165], v[208:211], v[24:27]
	v_mfma_f32_16x16x32_bf16 v[12:15], v[144:147], v[216:219], v[12:15]
	v_mfma_f32_16x16x32_bf16 v[8:11], v[162:165], v[216:219], v[8:11]
	v_mfma_f32_16x16x32_bf16 v[60:63], v[148:151], v[196:199], v[60:63]
	v_mfma_f32_16x16x32_bf16 v[56:59], v[166:169], v[196:199], v[56:59]
	v_mfma_f32_16x16x32_bf16 v[44:47], v[148:151], v[204:207], v[44:47]
	v_mfma_f32_16x16x32_bf16 v[40:43], v[166:169], v[204:207], v[40:43]
	v_mfma_f32_16x16x32_bf16 v[28:31], v[148:151], v[212:215], v[28:31]
	v_mfma_f32_16x16x32_bf16 v[24:27], v[166:169], v[212:215], v[24:27]
	v_mfma_f32_16x16x32_bf16 v[12:15], v[148:151], v[220:223], v[12:15]
	v_mfma_f32_16x16x32_bf16 v[8:11], v[166:169], v[220:223], v[8:11]
	s_setprio 0
	s_setprio 1
	v_mfma_f32_16x16x32_bf16 v[52:55], v[170:173], v[192:195], v[52:55]
	v_mfma_f32_16x16x32_bf16 v[48:51], v[184:187], v[192:195], v[48:51]
	v_mfma_f32_16x16x32_bf16 v[36:39], v[170:173], v[200:203], v[36:39]
	v_mfma_f32_16x16x32_bf16 v[32:35], v[184:187], v[200:203], v[32:35]
	v_mfma_f32_16x16x32_bf16 v[20:23], v[170:173], v[208:211], v[20:23]
	v_mfma_f32_16x16x32_bf16 v[16:19], v[184:187], v[208:211], v[16:19]
	v_mfma_f32_16x16x32_bf16 v[4:7], v[170:173], v[216:219], v[4:7]
	v_mfma_f32_16x16x32_bf16 v[0:3], v[184:187], v[216:219], v[0:3]
	v_mfma_f32_16x16x32_bf16 v[52:55], v[174:177], v[196:199], v[52:55]
	v_mfma_f32_16x16x32_bf16 v[48:51], v[188:191], v[196:199], v[48:51]
	v_mfma_f32_16x16x32_bf16 v[36:39], v[174:177], v[204:207], v[36:39]
	v_mfma_f32_16x16x32_bf16 v[32:35], v[188:191], v[204:207], v[32:35]
	v_mfma_f32_16x16x32_bf16 v[20:23], v[174:177], v[212:215], v[20:23]
	v_mfma_f32_16x16x32_bf16 v[16:19], v[188:191], v[212:215], v[16:19]
	v_mfma_f32_16x16x32_bf16 v[4:7], v[174:177], v[220:223], v[4:7]
	v_mfma_f32_16x16x32_bf16 v[0:3], v[188:191], v[220:223], v[0:3]
	s_setprio 0
	s_barrier
; #define PG8_STAGE(bufoff, gbase, voff) do { _Pragma("unroll") for (int _i = 0; _i < 2; ++_i) \
;         __builtin_amdgcn_global_load_lds((const unsigned*)((const char*)(gbase) + (voff)[_i]), (LAS unsigned*)(lds + (bufoff) + ldsw + _i * 8192), 16, 0, 0); } while (0)
; #define PG8_LDA(dst, b, h) do { _Pragma("unroll") for (int m = 0; m < 4; ++m) _Pragma("unroll") for (int k = 0; k < 2; ++k) dst[m][k] = *(const LAS bf16x8*)(lds + PG8_SA(b, h) + aoff + m * 2048 + k * 1024); } while (0)
; #define PG8_LDB(dst, b, h) do { _Pragma("unroll") for (int n = 0; n < 2; ++n) _Pragma("unroll") for (int k = 0; k < 2; ++k) dst[n][k] = *(const LAS bf16x8*)(lds + PG8_SB(b, h) + boff + n * 2048 + k * 1024); } while (0)
; #define PG8_MMA(ai, bj, At, Bt) do { __builtin_amdgcn_s_setprio(1); _Pragma("unroll") for (int m = 0; m < 4; ++m) _Pragma("unroll") for (int n = 0; n < 2; ++n) _Pragma("unroll") for (int k = 0; k < 2; ++k) \
;         acc[ai][bj][m][n] = __builtin_amdgcn_mfma_f32_16x16x32_bf16(Bt[n][k], At[m][k], acc[ai][bj][m][n], 0, 0, 0); __builtin_amdgcn_s_setprio(0); } while (0)
; #define PG8_WAIT_V(n) asm volatile("s_waitcnt vmcnt(" #n ")" ::: "memory")
; #define PG8_WAIT_L(n) asm volatile("s_waitcnt lgkmcnt(" #n ")" ::: "memory")
; #define PG8_BAR __builtin_amdgcn_s_barrier()
; #define PG8_SCHED __builtin_amdgcn_sched_barrier(0)
; template <class Epi>
; __device__ __forceinline__ void gemm_phase(LAS unsigned char* lds, const Gemm g, const StaticOrder& S, const Epi& E) {
;     ...
;             PG8_LDB(B0, 1, 0); PG8_LDB(B1, 1, 1); PG8_SCHED; PG8_LDA(At, 1, 0); PG8_STAGE(PG8_SA(0, 1), a2 + hsA, voffA);
;             PG8_WAIT_V(8); PG8_WAIT_L(0); PG8_BAR; PG8_MMA(0, 0, At, B0); PG8_MMA(0, 1, At, B1); PG8_BAR; PG8_SCHED;
;             PG8_LDA(At, 1, 1); PG8_STAGE(PG8_SB(1, 0), b3, voffB); PG8_STAGE(PG8_SB(1, 1), b3 + hsB, voffB); PG8_STAGE(PG8_SA(1, 0), a3, voffA);
;             PG8_WAIT_V(8); PG8_WAIT_L(0); PG8_BAR; PG8_MMA(1, 0, At, B0); PG8_MMA(1, 1, At, B1); PG8_BAR; PG8_SCHED;
;         }
	s_add_i32 s39, 0, 0x18000
	v_add_u32_e32 v160, s39, v153
	s_add_i32 s41, 0, 0x1c000
	ds_read_b128 v[144:147], v160
	ds_read_b128 v[148:151], v160 offset:1024
	ds_read_b128 v[162:165], v160 offset:2048
	ds_read_b128 v[166:169], v160 offset:3072
	v_add_u32_e32 v160, s41, v153
	ds_read_b128 v[170:173], v160
	ds_read_b128 v[174:177], v160 offset:1024
	ds_read_b128 v[184:187], v160 offset:2048
	ds_read_b128 v[188:191], v160 offset:3072
	s_add_u32 s52, s52, 0x40000
	s_addc_u32 s53, s53, 0
	s_mov_b32 m0, s17
	ds_read_b128 v[192:195], v157 offset:32768
	ds_read_b128 v[196:199], v157 offset:33792
	ds_read_b128 v[200:203], v157 offset:34816
	ds_read_b128 v[204:207], v157 offset:35840
	ds_read_b128 v[208:211], v157 offset:36864
	ds_read_b128 v[212:215], v157 offset:37888
	ds_read_b128 v[216:219], v157 offset:38912
	ds_read_b128 v[220:223], v157 offset:39936
	global_load_lds_dwordx4 v128, s[52:53]
	s_mov_b32 m0, s18
	s_nop 0
	global_load_lds_dwordx4 v132, s[52:53]
	s_waitcnt vmcnt(8)
	s_waitcnt lgkmcnt(0)
	s_barrier
	s_setprio 1
	s_waitcnt lgkmcnt(0)
	v_mfma_f32_16x16x32_bf16 v[124:127], v[144:147], v[192:195], v[124:127]
	v_mfma_f32_16x16x32_bf16 v[120:123], v[162:165], v[192:195], v[120:123]
	v_mfma_f32_16x16x32_bf16 v[108:111], v[144:147], v[200:203], v[108:111]
	v_mfma_f32_16x16x32_bf16 v[104:107], v[162:165], v[200:203], v[104:107]
	v_mfma_f32_16x16x32_bf16 v[92:95], v[144:147], v[208:211], v[92:95]
	v_mfma_f32_16x16x32_bf16 v[88:91], v[162:165], v[208:211], v[88:91]
	v_mfma_f32_16x16x32_bf16 v[76:79], v[144:147], v[216:219], v[76:79]
	v_mfma_f32_16x16x32_bf16 v[72:75], v[162:165], v[216:219], v[72:75]
	v_mfma_f32_16x16x32_bf16 v[124:127], v[148:151], v[196:199], v[124:127]
	v_mfma_f32_16x16x32_bf16 v[120:123], v[166:169], v[196:199], v[120:123]
	v_mfma_f32_16x16x32_bf16 v[108:111], v[148:151], v[204:207], v[108:111]
	v_mfma_f32_16x16x32_bf16 v[104:107], v[166:169], v[204:207], v[104:107]
	v_mfma_f32_16x16x32_bf16 v[92:95], v[148:151], v[212:215], v[92:95]
	v_mfma_f32_16x16x32_bf16 v[88:91], v[166:169], v[212:215], v[88:91]
	v_mfma_f32_16x16x32_bf16 v[76:79], v[148:151], v[220:223], v[76:79]
	v_mfma_f32_16x16x32_bf16 v[72:75], v[166:169], v[220:223], v[72:75]
	s_setprio 0
	s_setprio 1
	v_mfma_f32_16x16x32_bf16 v[116:119], v[170:173], v[192:195], v[116:119]
	v_mfma_f32_16x16x32_bf16 v[112:115], v[184:187], v[192:195], v[112:115]
	v_mfma_f32_16x16x32_bf16 v[100:103], v[170:173], v[200:203], v[100:103]
	v_mfma_f32_16x16x32_bf16 v[96:99], v[184:187], v[200:203], v[96:99]
	v_mfma_f32_16x16x32_bf16 v[84:87], v[170:173], v[208:211], v[84:87]
	v_mfma_f32_16x16x32_bf16 v[80:83], v[184:187], v[208:211], v[80:83]
	v_mfma_f32_16x16x32_bf16 v[68:71], v[170:173], v[216:219], v[68:71]
	v_mfma_f32_16x16x32_bf16 v[64:67], v[184:187], v[216:219], v[64:67]
	v_mfma_f32_16x16x32_bf16 v[116:119], v[174:177], v[196:199], v[116:119]
	v_mfma_f32_16x16x32_bf16 v[112:115], v[188:191], v[196:199], v[112:115]
	v_mfma_f32_16x16x32_bf16 v[100:103], v[174:177], v[204:207], v[100:103]
	v_mfma_f32_16x16x32_bf16 v[96:99], v[188:191], v[204:207], v[96:99]
	v_mfma_f32_16x16x32_bf16 v[84:87], v[174:177], v[212:215], v[84:87]
	v_mfma_f32_16x16x32_bf16 v[80:83], v[188:191], v[212:215], v[80:83]
	v_mfma_f32_16x16x32_bf16 v[68:71], v[174:177], v[220:223], v[68:71]
	v_mfma_f32_16x16x32_bf16 v[64:67], v[188:191], v[220:223], v[64:67]
	s_setprio 0
	s_barrier
	s_add_u32 s98, s50, 0x80
	s_addc_u32 s99, s51, 0
	s_add_u32 s100, s52, 0xfffc0080
	s_addc_u32 s101, s53, -1
	s_add_i32 s39, s39, s4
	s_mov_b32 m0, s39
	ds_read_b128 v[192:195], v157 offset:49152
	ds_read_b128 v[196:199], v157 offset:50176
	ds_read_b128 v[200:203], v157 offset:51200
	ds_read_b128 v[204:207], v157 offset:52224
	ds_read_b128 v[208:211], v157 offset:53248
	ds_read_b128 v[212:215], v157 offset:54272
	ds_read_b128 v[216:219], v157 offset:55296
	ds_read_b128 v[220:223], v157 offset:56320
	global_load_lds_dwordx4 v130, s[98:99]
	s_add_i32 m0, s39, 0x2000
	s_add_u32 s50, s50, 0x40080
	s_addc_u32 s51, s51, 0
	s_add_i32 s39, s41, s4
	global_load_lds_dwordx4 v134, s[98:99]
	s_mov_b32 m0, s39
	s_nop 0
	global_load_lds_dwordx4 v130, s[50:51]
	s_add_i32 m0, s39, 0x2000
	s_nop 0
	global_load_lds_dwordx4 v134, s[50:51]
	s_mov_b32 m0, s22
	s_nop 0
	global_load_lds_dwordx4 v128, s[100:101]
	s_mov_b32 m0, s23
	s_nop 0
	global_load_lds_dwordx4 v132, s[100:101]
	s_waitcnt vmcnt(8)
	s_waitcnt lgkmcnt(0)
	s_barrier
	s_setprio 1
	s_waitcnt lgkmcnt(0)
	v_mfma_f32_16x16x32_bf16 v[60:63], v[144:147], v[192:195], v[60:63]
	v_mfma_f32_16x16x32_bf16 v[56:59], v[162:165], v[192:195], v[56:59]
	v_mfma_f32_16x16x32_bf16 v[44:47], v[144:147], v[200:203], v[44:47]
	v_mfma_f32_16x16x32_bf16 v[40:43], v[162:165], v[200:203], v[40:43]
	v_mfma_f32_16x16x32_bf16 v[28:31], v[144:147], v[208:211], v[28:31]
	v_mfma_f32_16x16x32_bf16 v[24:27], v[162:165], v[208:211], v[24:27]
	v_mfma_f32_16x16x32_bf16 v[12:15], v[144:147], v[216:219], v[12:15]
	v_mfma_f32_16x16x32_bf16 v[8:11], v[162:165], v[216:219], v[8:11]
	v_mfma_f32_16x16x32_bf16 v[60:63], v[148:151], v[196:199], v[60:63]
	v_mfma_f32_16x16x32_bf16 v[56:59], v[166:169], v[196:199], v[56:59]
	v_mfma_f32_16x16x32_bf16 v[44:47], v[148:151], v[204:207], v[44:47]
	v_mfma_f32_16x16x32_bf16 v[40:43], v[166:169], v[204:207], v[40:43]
	v_mfma_f32_16x16x32_bf16 v[28:31], v[148:151], v[212:215], v[28:31]
	v_mfma_f32_16x16x32_bf16 v[24:27], v[166:169], v[212:215], v[24:27]
	v_mfma_f32_16x16x32_bf16 v[12:15], v[148:151], v[220:223], v[12:15]
	v_mfma_f32_16x16x32_bf16 v[8:11], v[166:169], v[220:223], v[8:11]
	s_setprio 0
	s_setprio 1
	v_mfma_f32_16x16x32_bf16 v[52:55], v[170:173], v[192:195], v[52:55]
	v_mfma_f32_16x16x32_bf16 v[48:51], v[184:187], v[192:195], v[48:51]
	v_mfma_f32_16x16x32_bf16 v[36:39], v[170:173], v[200:203], v[36:39]
	v_mfma_f32_16x16x32_bf16 v[32:35], v[184:187], v[200:203], v[32:35]
	v_mfma_f32_16x16x32_bf16 v[20:23], v[170:173], v[208:211], v[20:23]
	v_mfma_f32_16x16x32_bf16 v[16:19], v[184:187], v[208:211], v[16:19]
	v_mfma_f32_16x16x32_bf16 v[4:7], v[170:173], v[216:219], v[4:7]
	v_mfma_f32_16x16x32_bf16 v[0:3], v[184:187], v[216:219], v[0:3]
	v_mfma_f32_16x16x32_bf16 v[52:55], v[174:177], v[196:199], v[52:55]
	v_mfma_f32_16x16x32_bf16 v[48:51], v[188:191], v[196:199], v[48:51]
	v_mfma_f32_16x16x32_bf16 v[36:39], v[174:177], v[204:207], v[36:39]
	v_mfma_f32_16x16x32_bf16 v[32:35], v[188:191], v[204:207], v[32:35]
	v_mfma_f32_16x16x32_bf16 v[20:23], v[174:177], v[212:215], v[20:23]
	v_mfma_f32_16x16x32_bf16 v[16:19], v[188:191], v[212:215], v[16:19]
	v_mfma_f32_16x16x32_bf16 v[4:7], v[174:177], v[220:223], v[4:7]
	v_mfma_f32_16x16x32_bf16 v[0:3], v[188:191], v[220:223], v[0:3]
	s_setprio 0
	s_barrier
	s_add_i32 s35, s35, 2
	s_add_u32 s48, s48, 0x100
	s_addc_u32 s49, s49, 0
	s_add_u32 s13, s13, 0x100
	s_addc_u32 s34, s34, 0
	s_cmp_gt_u32 s35, 13
	s_cbranch_scc0 .LBB0_1234
	s_and_b64 vcc, exec, s[26:27]
	s_cbranch_vccz .LBB0_1237
	s_barrier

; #define PG8_STAGE(bufoff, gbase, voff) do { _Pragma("unroll") for (int _i = 0; _i < 2; ++_i) \
;         __builtin_amdgcn_global_load_lds((const unsigned*)((const char*)(gbase) + (voff)[_i]), (LAS unsigned*)(lds + (bufoff) + ldsw + _i * 8192), 16, 0, 0); } while (0)
; #define PG8_LDA(dst, b, h) do { _Pragma("unroll") for (int m = 0; m < 4; ++m) _Pragma("unroll") for (int k = 0; k < 2; ++k) dst[m][k] = *(const LAS bf16x8*)(lds + PG8_SA(b, h) + aoff + m * 2048 + k * 1024); } while (0)
; #define PG8_LDB(dst, b, h) do { _Pragma("unroll") for (int n = 0; n < 2; ++n) _Pragma("unroll") for (int k = 0; k < 2; ++k) dst[n][k] = *(const LAS bf16x8*)(lds + PG8_SB(b, h) + boff + n * 2048 + k * 1024); } while (0)
; #define PG8_MMA(ai, bj, At, Bt) do { __builtin_amdgcn_s_setprio(1); _Pragma("unroll") for (int m = 0; m < 4; ++m) _Pragma("unroll") for (int n = 0; n < 2; ++n) _Pragma("unroll") for (int k = 0; k < 2; ++k) \
;         acc[ai][bj][m][n] = __builtin_amdgcn_mfma_f32_16x16x32_bf16(Bt[n][k], At[m][k], acc[ai][bj][m][n], 0, 0, 0); __builtin_amdgcn_s_setprio(0); } while (0)
; #define PG8_WAIT_V(n) asm volatile("s_waitcnt vmcnt(" #n ")" ::: "memory")
; template <class Epi>
; __device__ __forceinline__ void gemm_phase(LAS unsigned char* lds, const Gemm g, const StaticOrder& S, const Epi& E) {
;     ...
;         for (int t = 0; t < nt; t += 2) {
;             const bool last = (t == nt - 2);
;             if constexpr (Epi::HAS_MID) { if (t == nt1) E.mid(acc, cur, wr, wc, fr, fq); }
;             const char* a1 = cA + ((Epi::HAS_MID && t >= nt1) ? dA2 : 0) + (size_t)(t + 1) * kstep;
;             const char* a2 = last ? nA : cA + ((Epi::HAS_MID && t + 2 >= nt1) ? dA2 : 0) + (size_t)(t + 2) * kstep; const char* b2 = last ? nB : cB + ((Epi::HAS_MID && t + 2 >= nt1) ? dB2 : 0) + (size_t)(t + 2) * kstep;
;             const char* a3 = a2 + kstep; const char* b3 = b2 + kstep;
;             PG8_LDB(B0, 0, 0); PG8_LDB(B1, 0, 1); PG8_SCHED; PG8_LDA(At, 0, 0); PG8_STAGE(PG8_SA(1, 1), a1 + hsA, voffA);
;             PG8_WAIT_V(8); PG8_WAIT_L(0); PG8_BAR; PG8_MMA(0, 0, At, B0); PG8_MMA(0, 1, At, B1); PG8_BAR; PG8_SCHED;
;             PG8_LDA(At, 0, 1); PG8_STAGE(PG8_SB(0, 0), b2, voffB); PG8_STAGE(PG8_SB(0, 1), b2 + hsB, voffB); PG8_STAGE(PG8_SA(0, 0), a2, voffA);
;             PG8_WAIT_V(8); PG8_WAIT_L(0); PG8_BAR; PG8_MMA(1, 0, At, B0); PG8_MMA(1, 1, At, B1); PG8_BAR; PG8_SCHED;
.LBB0_1350:
	ds_read_b128 v[144:147], v155
	ds_read_b128 v[148:151], v155 offset:1024
	ds_read_b128 v[162:165], v155 offset:2048
	ds_read_b128 v[166:169], v155 offset:3072
	ds_read_b128 v[170:173], v156
	ds_read_b128 v[174:177], v156 offset:1024
	ds_read_b128 v[184:187], v156 offset:2048
	ds_read_b128 v[188:191], v156 offset:3072
	s_add_u32 s40, s38, 0xfffc0080
	s_addc_u32 s41, s39, -1
	s_cmp_eq_u32 s48, 12
	s_cselect_b32 s43, s25, s41
	s_cselect_b32 s42, s44, s40
	s_cselect_b32 s41, s15, s47
	s_cselect_b32 s40, s45, s46
	s_add_i32 m0, s17, 0xc000
	ds_read_b128 v[192:195], v157
	ds_read_b128 v[196:199], v157 offset:1024
	ds_read_b128 v[200:203], v157 offset:2048
	ds_read_b128 v[204:207], v157 offset:3072
	ds_read_b128 v[208:211], v157 offset:4096
	ds_read_b128 v[212:215], v157 offset:5120
	ds_read_b128 v[216:219], v157 offset:6144
	ds_read_b128 v[220:223], v157 offset:7168
	global_load_lds_dwordx4 v136, s[38:39]
	s_add_i32 m0, s17, 0xe000
	s_nop 0
	global_load_lds_dwordx4 v138, s[38:39]
	s_waitcnt vmcnt(8)
	s_waitcnt lgkmcnt(0)
	s_barrier
	s_setprio 1
	s_waitcnt lgkmcnt(0)
	v_mfma_f32_16x16x32_bf16 v[124:127], v[144:147], v[192:195], v[124:127]
	v_mfma_f32_16x16x32_bf16 v[120:123], v[162:165], v[192:195], v[120:123]
	v_mfma_f32_16x16x32_bf16 v[108:111], v[144:147], v[200:203], v[108:111]
	v_mfma_f32_16x16x32_bf16 v[104:107], v[162:165], v[200:203], v[104:107]
	v_mfma_f32_16x16x32_bf16 v[92:95], v[144:147], v[208:211], v[92:95]
	v_mfma_f32_16x16x32_bf16 v[88:91], v[162:165], v[208:211], v[88:91]
	v_mfma_f32_16x16x32_bf16 v[76:79], v[144:147], v[216:219], v[76:79]
	v_mfma_f32_16x16x32_bf16 v[72:75], v[162:165], v[216:219], v[72:75]
	v_mfma_f32_16x16x32_bf16 v[124:127], v[148:151], v[196:199], v[124:127]
	v_mfma_f32_16x16x32_bf16 v[120:123], v[166:169], v[196:199], v[120:123]
	v_mfma_f32_16x16x32_bf16 v[108:111], v[148:151], v[204:207], v[108:111]
	v_mfma_f32_16x16x32_bf16 v[104:107], v[166:169], v[204:207], v[104:107]
	v_mfma_f32_16x16x32_bf16 v[92:95], v[148:151], v[212:215], v[92:95]
	v_mfma_f32_16x16x32_bf16 v[88:91], v[166:169], v[212:215], v[88:91]
	v_mfma_f32_16x16x32_bf16 v[76:79], v[148:151], v[220:223], v[76:79]
	v_mfma_f32_16x16x32_bf16 v[72:75], v[166:169], v[220:223], v[72:75]
	s_setprio 0
	s_setprio 1
	v_mfma_f32_16x16x32_bf16 v[116:119], v[170:173], v[192:195], v[116:119]
	v_mfma_f32_16x16x32_bf16 v[112:115], v[184:187], v[192:195], v[112:115]
	v_mfma_f32_16x16x32_bf16 v[100:103], v[170:173], v[200:203], v[100:103]
	v_mfma_f32_16x16x32_bf16 v[96:99], v[184:187], v[200:203], v[96:99]
	v_mfma_f32_16x16x32_bf16 v[84:87], v[170:173], v[208:211], v[84:87]
	v_mfma_f32_16x16x32_bf16 v[80:83], v[184:187], v[208:211], v[80:83]
	v_mfma_f32_16x16x32_bf16 v[68:71], v[170:173], v[216:219], v[68:71]
	v_mfma_f32_16x16x32_bf16 v[64:67], v[184:187], v[216:219], v[64:67]
	v_mfma_f32_16x16x32_bf16 v[116:119], v[174:177], v[196:199], v[116:119]
	v_mfma_f32_16x16x32_bf16 v[112:115], v[188:191], v[196:199], v[112:115]
	v_mfma_f32_16x16x32_bf16 v[100:103], v[174:177], v[204:207], v[100:103]
	v_mfma_f32_16x16x32_bf16 v[96:99], v[188:191], v[204:207], v[96:99]
	v_mfma_f32_16x16x32_bf16 v[84:87], v[174:177], v[212:215], v[84:87]
	v_mfma_f32_16x16x32_bf16 v[80:83], v[188:191], v[212:215], v[80:83]
	v_mfma_f32_16x16x32_bf16 v[68:71], v[174:177], v[220:223], v[68:71]
	v_mfma_f32_16x16x32_bf16 v[64:67], v[188:191], v[220:223], v[64:67]
	s_setprio 0
	s_barrier
	s_add_i32 s49, s30, s4
	s_mov_b32 m0, s49
	ds_read_b128 v[192:195], v157 offset:16384
	ds_read_b128 v[196:199], v157 offset:17408
	ds_read_b128 v[200:203], v157 offset:18432
	ds_read_b128 v[204:207], v157 offset:19456
	ds_read_b128 v[208:211], v157 offset:20480
	ds_read_b128 v[212:215], v157 offset:21504
	ds_read_b128 v[216:219], v157 offset:22528
	ds_read_b128 v[220:223], v157 offset:23552
	global_load_lds_dwordx4 v132, s[40:41]
	s_add_i32 m0, s49, 0x2000
	s_add_u32 s50, s40, 0x40000
	s_addc_u32 s51, s41, 0
	s_add_i32 s49, s31, s4
	global_load_lds_dwordx4 v128, s[40:41]
	s_mov_b32 m0, s49
	s_nop 0
	global_load_lds_dwordx4 v132, s[50:51]
	s_add_i32 m0, s49, 0x2000
	s_nop 0
	global_load_lds_dwordx4 v128, s[50:51]
	s_mov_b32 m0, s17
	s_nop 0
	global_load_lds_dwordx4 v134, s[42:43]
	s_mov_b32 m0, s18
	s_nop 0
	global_load_lds_dwordx4 v130, s[42:43]
	s_waitcnt vmcnt(8)
	s_waitcnt lgkmcnt(0)
	s_barrier
	s_setprio 1
	s_waitcnt lgkmcnt(0)
	v_mfma_f32_16x16x32_bf16 v[60:63], v[144:147], v[192:195], v[60:63]
	v_mfma_f32_16x16x32_bf16 v[56:59], v[162:165], v[192:195], v[56:59]
	v_mfma_f32_16x16x32_bf16 v[44:47], v[144:147], v[200:203], v[44:47]
	v_mfma_f32_16x16x32_bf16 v[40:43], v[162:165], v[200:203], v[40:43]
	v_mfma_f32_16x16x32_bf16 v[28:31], v[144:147], v[208:211], v[28:31]
	v_mfma_f32_16x16x32_bf16 v[24:27], v[162:165], v[208:211], v[24:27]
	v_mfma_f32_16x16x32_bf16 v[12:15], v[144:147], v[216:219], v[12:15]
	v_mfma_f32_16x16x32_bf16 v[8:11], v[162:165], v[216:219], v[8:11]
	v_mfma_f32_16x16x32_bf16 v[60:63], v[148:151], v[196:199], v[60:63]
	v_mfma_f32_16x16x32_bf16 v[56:59], v[166:169], v[196:199], v[56:59]
	v_mfma_f32_16x16x32_bf16 v[44:47], v[148:151], v[204:207], v[44:47]
	v_mfma_f32_16x16x32_bf16 v[40:43], v[166:169], v[204:207], v[40:43]
	v_mfma_f32_16x16x32_bf16 v[28:31], v[148:151], v[212:215], v[28:31]
	v_mfma_f32_16x16x32_bf16 v[24:27], v[166:169], v[212:215], v[24:27]
	v_mfma_f32_16x16x32_bf16 v[12:15], v[148:151], v[220:223], v[12:15]
	v_mfma_f32_16x16x32_bf16 v[8:11], v[166:169], v[220:223], v[8:11]
	s_setprio 0
	s_setprio 1
	v_mfma_f32_16x16x32_bf16 v[52:55], v[170:173], v[192:195], v[52:55]
	v_mfma_f32_16x16x32_bf16 v[48:51], v[184:187], v[192:195], v[48:51]
	v_mfma_f32_16x16x32_bf16 v[36:39], v[170:173], v[200:203], v[36:39]
	v_mfma_f32_16x16x32_bf16 v[32:35], v[184:187], v[200:203], v[32:35]
	v_mfma_f32_16x16x32_bf16 v[20:23], v[170:173], v[208:211], v[20:23]
	v_mfma_f32_16x16x32_bf16 v[16:19], v[184:187], v[208:211], v[16:19]
	v_mfma_f32_16x16x32_bf16 v[4:7], v[170:173], v[216:219], v[4:7]
	v_mfma_f32_16x16x32_bf16 v[0:3], v[184:187], v[216:219], v[0:3]
	v_mfma_f32_16x16x32_bf16 v[52:55], v[174:177], v[196:199], v[52:55]
	v_mfma_f32_16x16x32_bf16 v[48:51], v[188:191], v[196:199], v[48:51]
	v_mfma_f32_16x16x32_bf16 v[36:39], v[174:177], v[204:207], v[36:39]
	v_mfma_f32_16x16x32_bf16 v[32:35], v[188:191], v[204:207], v[32:35]
	v_mfma_f32_16x16x32_bf16 v[20:23], v[174:177], v[212:215], v[20:23]
	v_mfma_f32_16x16x32_bf16 v[16:19], v[188:191], v[212:215], v[16:19]
	v_mfma_f32_16x16x32_bf16 v[4:7], v[174:177], v[220:223], v[4:7]
	v_mfma_f32_16x16x32_bf16 v[0:3], v[188:191], v[220:223], v[0:3]
	s_setprio 0
	s_barrier
; #define PG8_STAGE(bufoff, gbase, voff) do { _Pragma("unroll") for (int _i = 0; _i < 2; ++_i) \
;         __builtin_amdgcn_global_load_lds((const unsigned*)((const char*)(gbase) + (voff)[_i]), (LAS unsigned*)(lds + (bufoff) + ldsw + _i * 8192), 16, 0, 0); } while (0)
; #define PG8_LDA(dst, b, h) do { _Pragma("unroll") for (int m = 0; m < 4; ++m) _Pragma("unroll") for (int k = 0; k < 2; ++k) dst[m][k] = *(const LAS bf16x8*)(lds + PG8_SA(b, h) + aoff + m * 2048 + k * 1024); } while (0)
; #define PG8_LDB(dst, b, h) do { _Pragma("unroll") for (int n = 0; n < 2; ++n) _Pragma("unroll") for (int k = 0; k < 2; ++k) dst[n][k] = *(const LAS bf16x8*)(lds + PG8_SB(b, h) + boff + n * 2048 + k * 1024); } while (0)
; #define PG8_MMA(ai, bj, At, Bt) do { __builtin_amdgcn_s_setprio(1); _Pragma("unroll") for (int m = 0; m < 4; ++m) _Pragma("unroll") for (int n = 0; n < 2; ++n) _Pragma("unroll") for (int k = 0; k < 2; ++k) \
;         acc[ai][bj][m][n] = __builtin_amdgcn_mfma_f32_16x16x32_bf16(Bt[n][k], At[m][k], acc[ai][bj][m][n], 0, 0, 0); __builtin_amdgcn_s_setprio(0); } while (0)
; #define PG8_WAIT_V(n) asm volatile("s_waitcnt vmcnt(" #n ")" ::: "memory")
; #define PG8_WAIT_L(n) asm volatile("s_waitcnt lgkmcnt(" #n ")" ::: "memory")
; #define PG8_BAR __builtin_amdgcn_s_barrier()
; #define PG8_SCHED __builtin_amdgcn_sched_barrier(0)
; template <class Epi>
; __device__ __forceinline__ void gemm_phase(LAS unsigned char* lds, const Gemm g, const StaticOrder& S, const Epi& E) {
;     ...
;             PG8_LDB(B0, 1, 0); PG8_LDB(B1, 1, 1); PG8_SCHED; PG8_LDA(At, 1, 0); PG8_STAGE(PG8_SA(0, 1), a2 + hsA, voffA);
;             PG8_WAIT_V(8); PG8_WAIT_L(0); PG8_BAR; PG8_MMA(0, 0, At, B0); PG8_MMA(0, 1, At, B1); PG8_BAR; PG8_SCHED;
;             PG8_LDA(At, 1, 1); PG8_STAGE(PG8_SB(1, 0), b3, voffB); PG8_STAGE(PG8_SB(1, 1), b3 + hsB, voffB); PG8_STAGE(PG8_SA(1, 0), a3, voffA);
;             PG8_WAIT_V(8); PG8_WAIT_L(0); PG8_BAR; PG8_MMA(1, 0, At, B0); PG8_MMA(1, 1, At, B1); PG8_BAR; PG8_SCHED;
;         }
;         if (wr == 0) PG8_BAR;
	s_add_i32 s49, 0, 0x18000
	v_add_u32_e32 v159, s49, v153
	s_add_i32 s50, 0, 0x1c000
	ds_read_b128 v[144:147], v159
	ds_read_b128 v[148:151], v159 offset:1024
	ds_read_b128 v[162:165], v159 offset:2048
	ds_read_b128 v[166:169], v159 offset:3072
	v_add_u32_e32 v159, s50, v153
	ds_read_b128 v[170:173], v159
	ds_read_b128 v[174:177], v159 offset:1024
	ds_read_b128 v[184:187], v159 offset:2048
	ds_read_b128 v[188:191], v159 offset:3072
	s_add_u32 s42, s42, 0x40000
	s_addc_u32 s43, s43, 0
	s_mov_b32 m0, s19
	ds_read_b128 v[192:195], v157 offset:32768
	ds_read_b128 v[196:199], v157 offset:33792
	ds_read_b128 v[200:203], v157 offset:34816
	ds_read_b128 v[204:207], v157 offset:35840
	ds_read_b128 v[208:211], v157 offset:36864
	ds_read_b128 v[212:215], v157 offset:37888
	ds_read_b128 v[216:219], v157 offset:38912
	ds_read_b128 v[220:223], v157 offset:39936
	global_load_lds_dwordx4 v134, s[42:43]
	s_mov_b32 m0, s22
	s_nop 0
	global_load_lds_dwordx4 v130, s[42:43]
	s_waitcnt vmcnt(8)
	s_waitcnt lgkmcnt(0)
	s_barrier
	s_setprio 1
	s_waitcnt lgkmcnt(0)
	v_mfma_f32_16x16x32_bf16 v[124:127], v[144:147], v[192:195], v[124:127]
	v_mfma_f32_16x16x32_bf16 v[120:123], v[162:165], v[192:195], v[120:123]
	v_mfma_f32_16x16x32_bf16 v[108:111], v[144:147], v[200:203], v[108:111]
	v_mfma_f32_16x16x32_bf16 v[104:107], v[162:165], v[200:203], v[104:107]
	v_mfma_f32_16x16x32_bf16 v[92:95], v[144:147], v[208:211], v[92:95]
	v_mfma_f32_16x16x32_bf16 v[88:91], v[162:165], v[208:211], v[88:91]
	v_mfma_f32_16x16x32_bf16 v[76:79], v[144:147], v[216:219], v[76:79]
	v_mfma_f32_16x16x32_bf16 v[72:75], v[162:165], v[216:219], v[72:75]
	v_mfma_f32_16x16x32_bf16 v[124:127], v[148:151], v[196:199], v[124:127]
	v_mfma_f32_16x16x32_bf16 v[120:123], v[166:169], v[196:199], v[120:123]
	v_mfma_f32_16x16x32_bf16 v[108:111], v[148:151], v[204:207], v[108:111]
	v_mfma_f32_16x16x32_bf16 v[104:107], v[166:169], v[204:207], v[104:107]
	v_mfma_f32_16x16x32_bf16 v[92:95], v[148:151], v[212:215], v[92:95]
	v_mfma_f32_16x16x32_bf16 v[88:91], v[166:169], v[212:215], v[88:91]
	v_mfma_f32_16x16x32_bf16 v[76:79], v[148:151], v[220:223], v[76:79]
	v_mfma_f32_16x16x32_bf16 v[72:75], v[166:169], v[220:223], v[72:75]
	s_setprio 0
	s_setprio 1
	v_mfma_f32_16x16x32_bf16 v[116:119], v[170:173], v[192:195], v[116:119]
	v_mfma_f32_16x16x32_bf16 v[112:115], v[184:187], v[192:195], v[112:115]
	v_mfma_f32_16x16x32_bf16 v[100:103], v[170:173], v[200:203], v[100:103]
	v_mfma_f32_16x16x32_bf16 v[96:99], v[184:187], v[200:203], v[96:99]
	v_mfma_f32_16x16x32_bf16 v[84:87], v[170:173], v[208:211], v[84:87]
	v_mfma_f32_16x16x32_bf16 v[80:83], v[184:187], v[208:211], v[80:83]
	v_mfma_f32_16x16x32_bf16 v[68:71], v[170:173], v[216:219], v[68:71]
	v_mfma_f32_16x16x32_bf16 v[64:67], v[184:187], v[216:219], v[64:67]
	v_mfma_f32_16x16x32_bf16 v[116:119], v[174:177], v[196:199], v[116:119]
	v_mfma_f32_16x16x32_bf16 v[112:115], v[188:191], v[196:199], v[112:115]
	v_mfma_f32_16x16x32_bf16 v[100:103], v[174:177], v[204:207], v[100:103]
	v_mfma_f32_16x16x32_bf16 v[96:99], v[188:191], v[204:207], v[96:99]
	v_mfma_f32_16x16x32_bf16 v[84:87], v[174:177], v[212:215], v[84:87]
	v_mfma_f32_16x16x32_bf16 v[80:83], v[188:191], v[212:215], v[80:83]
	v_mfma_f32_16x16x32_bf16 v[68:71], v[174:177], v[220:223], v[68:71]
	v_mfma_f32_16x16x32_bf16 v[64:67], v[188:191], v[220:223], v[64:67]
	s_setprio 0
	s_barrier
	s_add_u32 s98, s40, 0x80
	s_addc_u32 s99, s41, 0
	s_add_u32 s100, s42, 0xfffc0080
	s_addc_u32 s101, s43, -1
	s_add_i32 s42, s49, s4
	s_mov_b32 m0, s42
	ds_read_b128 v[192:195], v157 offset:49152
	ds_read_b128 v[196:199], v157 offset:50176
	ds_read_b128 v[200:203], v157 offset:51200
	ds_read_b128 v[204:207], v157 offset:52224
	ds_read_b128 v[208:211], v157 offset:53248
	ds_read_b128 v[212:215], v157 offset:54272
	ds_read_b128 v[216:219], v157 offset:55296
	ds_read_b128 v[220:223], v157 offset:56320
	global_load_lds_dwordx4 v132, s[98:99]
	s_add_i32 m0, s42, 0x2000
	s_add_u32 s40, s40, 0x40080
	s_addc_u32 s41, s41, 0
	s_add_i32 s42, s50, s4
	global_load_lds_dwordx4 v128, s[98:99]
	s_mov_b32 m0, s42
	s_nop 0
	global_load_lds_dwordx4 v132, s[40:41]
	s_add_i32 m0, s42, 0x2000
	s_nop 0
	global_load_lds_dwordx4 v128, s[40:41]
	s_mov_b32 m0, s0
	s_nop 0
	global_load_lds_dwordx4 v134, s[100:101]
	s_mov_b32 m0, s1
	s_nop 0
	global_load_lds_dwordx4 v130, s[100:101]
	s_waitcnt vmcnt(8)
	s_waitcnt lgkmcnt(0)
	s_barrier
	s_setprio 1
	s_waitcnt lgkmcnt(0)
	v_mfma_f32_16x16x32_bf16 v[60:63], v[144:147], v[192:195], v[60:63]
	v_mfma_f32_16x16x32_bf16 v[56:59], v[162:165], v[192:195], v[56:59]
	v_mfma_f32_16x16x32_bf16 v[44:47], v[144:147], v[200:203], v[44:47]
	v_mfma_f32_16x16x32_bf16 v[40:43], v[162:165], v[200:203], v[40:43]
	v_mfma_f32_16x16x32_bf16 v[28:31], v[144:147], v[208:211], v[28:31]
	v_mfma_f32_16x16x32_bf16 v[24:27], v[162:165], v[208:211], v[24:27]
	v_mfma_f32_16x16x32_bf16 v[12:15], v[144:147], v[216:219], v[12:15]
	v_mfma_f32_16x16x32_bf16 v[8:11], v[162:165], v[216:219], v[8:11]
	v_mfma_f32_16x16x32_bf16 v[60:63], v[148:151], v[196:199], v[60:63]
	v_mfma_f32_16x16x32_bf16 v[56:59], v[166:169], v[196:199], v[56:59]
	v_mfma_f32_16x16x32_bf16 v[44:47], v[148:151], v[204:207], v[44:47]
	v_mfma_f32_16x16x32_bf16 v[40:43], v[166:169], v[204:207], v[40:43]
	v_mfma_f32_16x16x32_bf16 v[28:31], v[148:151], v[212:215], v[28:31]
	v_mfma_f32_16x16x32_bf16 v[24:27], v[166:169], v[212:215], v[24:27]
	v_mfma_f32_16x16x32_bf16 v[12:15], v[148:151], v[220:223], v[12:15]
	v_mfma_f32_16x16x32_bf16 v[8:11], v[166:169], v[220:223], v[8:11]
	s_setprio 0
	s_setprio 1
	v_mfma_f32_16x16x32_bf16 v[52:55], v[170:173], v[192:195], v[52:55]
	v_mfma_f32_16x16x32_bf16 v[48:51], v[184:187], v[192:195], v[48:51]
	v_mfma_f32_16x16x32_bf16 v[36:39], v[170:173], v[200:203], v[36:39]
	v_mfma_f32_16x16x32_bf16 v[32:35], v[184:187], v[200:203], v[32:35]
	v_mfma_f32_16x16x32_bf16 v[20:23], v[170:173], v[208:211], v[20:23]
	v_mfma_f32_16x16x32_bf16 v[16:19], v[184:187], v[208:211], v[16:19]
	v_mfma_f32_16x16x32_bf16 v[4:7], v[170:173], v[216:219], v[4:7]
	v_mfma_f32_16x16x32_bf16 v[0:3], v[184:187], v[216:219], v[0:3]
	v_mfma_f32_16x16x32_bf16 v[52:55], v[174:177], v[196:199], v[52:55]
	v_mfma_f32_16x16x32_bf16 v[48:51], v[188:191], v[196:199], v[48:51]
	v_mfma_f32_16x16x32_bf16 v[36:39], v[174:177], v[204:207], v[36:39]
	v_mfma_f32_16x16x32_bf16 v[32:35], v[188:191], v[204:207], v[32:35]
	v_mfma_f32_16x16x32_bf16 v[20:23], v[174:177], v[212:215], v[20:23]
	v_mfma_f32_16x16x32_bf16 v[16:19], v[188:191], v[212:215], v[16:19]
	v_mfma_f32_16x16x32_bf16 v[4:7], v[174:177], v[220:223], v[4:7]
	v_mfma_f32_16x16x32_bf16 v[0:3], v[188:191], v[220:223], v[0:3]
	s_setprio 0
	s_barrier
	s_add_i32 s48, s48, 2
	s_add_u32 s38, s38, 0x100
	s_addc_u32 s39, s39, 0
	s_add_u32 s46, s46, 0x100
	s_addc_u32 s47, s47, 0
	s_cmp_gt_u32 s48, 13
	s_cbranch_scc0 .LBB0_1350
	s_and_b64 vcc, exec, s[12:13]
	s_cbranch_vccz .LBB0_1353
	s_barrier

; #define PG8_STAGE(bufoff, gbase, voff) do { _Pragma("unroll") for (int _i = 0; _i < 2; ++_i) \
;         __builtin_amdgcn_global_load_lds((const unsigned*)((const char*)(gbase) + (voff)[_i]), (LAS unsigned*)(lds + (bufoff) + ldsw + _i * 8192), 16, 0, 0); } while (0)
; #define PG8_LDA(dst, b, h) do { _Pragma("unroll") for (int m = 0; m < 4; ++m) _Pragma("unroll") for (int k = 0; k < 2; ++k) dst[m][k] = *(const LAS bf16x8*)(lds + PG8_SA(b, h) + aoff + m * 2048 + k * 1024); } while (0)
; #define PG8_LDB(dst, b, h) do { _Pragma("unroll") for (int n = 0; n < 2; ++n) _Pragma("unroll") for (int k = 0; k < 2; ++k) dst[n][k] = *(const LAS bf16x8*)(lds + PG8_SB(b, h) + boff + n * 2048 + k * 1024); } while (0)
; #define PG8_MMA(ai, bj, At, Bt) do { __builtin_amdgcn_s_setprio(1); _Pragma("unroll") for (int m = 0; m < 4; ++m) _Pragma("unroll") for (int n = 0; n < 2; ++n) _Pragma("unroll") for (int k = 0; k < 2; ++k) \
;         acc[ai][bj][m][n] = __builtin_amdgcn_mfma_f32_16x16x32_bf16(Bt[n][k], At[m][k], acc[ai][bj][m][n], 0, 0, 0); __builtin_amdgcn_s_setprio(0); } while (0)
; #define PG8_WAIT_V(n) asm volatile("s_waitcnt vmcnt(" #n ")" ::: "memory")
; #define PG8_BAR __builtin_amdgcn_s_barrier()
; template <class Epi>
; __device__ __forceinline__ void gemm_phase(LAS unsigned char* lds, const Gemm g, const StaticOrder& S, const Epi& E) {
;     ...
;             const bool last = (t == nt - 2);
;             if constexpr (Epi::HAS_MID) { if (t == nt1) E.mid(acc, cur, wr, wc, fr, fq); }
;             const char* a1 = cA + ((Epi::HAS_MID && t >= nt1) ? dA2 : 0) + (size_t)(t + 1) * kstep;
;             const char* a2 = last ? nA : cA + ((Epi::HAS_MID && t + 2 >= nt1) ? dA2 : 0) + (size_t)(t + 2) * kstep; const char* b2 = last ? nB : cB + ((Epi::HAS_MID && t + 2 >= nt1) ? dB2 : 0) + (size_t)(t + 2) * kstep;
;             const char* a3 = a2 + kstep; const char* b3 = b2 + kstep;
;             PG8_LDB(B0, 0, 0); PG8_LDB(B1, 0, 1); PG8_SCHED; PG8_LDA(At, 0, 0); PG8_STAGE(PG8_SA(1, 1), a1 + hsA, voffA);
;             PG8_WAIT_V(8); PG8_WAIT_L(0); PG8_BAR; PG8_MMA(0, 0, At, B0); PG8_MMA(0, 1, At, B1); PG8_BAR; PG8_SCHED;
;             PG8_LDA(At, 0, 1); PG8_STAGE(PG8_SB(0, 0), b2, voffB); PG8_STAGE(PG8_SB(0, 1), b2 + hsB, voffB); PG8_STAGE(PG8_SA(0, 0), a2, voffA);
;             PG8_WAIT_V(8); PG8_WAIT_L(0); PG8_BAR; PG8_MMA(1, 0, At, B0); PG8_MMA(1, 1, At, B1); PG8_BAR; PG8_SCHED;
.LBB0_1433:
	ds_read_b128 v[144:147], v202
	ds_read_b128 v[148:151], v202 offset:1024
	ds_read_b128 v[152:155], v202 offset:2048
	ds_read_b128 v[156:159], v202 offset:3072
	ds_read_b128 v[160:163], v203
	ds_read_b128 v[164:167], v203 offset:1024
	ds_read_b128 v[168:171], v203 offset:2048
	ds_read_b128 v[172:175], v203 offset:3072
	s_add_u32 s34, s26, 0x100
	s_addc_u32 s35, s27, 0
	s_cmp_eq_u32 s51, 40
	s_cselect_b32 s39, s1, s35
	s_cselect_b32 s38, s0, s34
	s_cselect_b32 s37, s23, s50
	s_cselect_b32 s36, s22, s25
	s_add_i32 m0, s17, 0xc000
	ds_read_b128 v[216:219], v204
	ds_read_b128 v[220:223], v204 offset:1024
	ds_read_b128 v[224:227], v204 offset:2048
	ds_read_b128 v[228:231], v204 offset:3072
	ds_read_b128 v[232:235], v204 offset:4096
	ds_read_b128 v[236:239], v204 offset:5120
	ds_read_b128 v[240:243], v204 offset:6144
	ds_read_b128 v[244:247], v204 offset:7168
	global_load_lds_dwordx4 v136, s[26:27]
	s_add_i32 m0, s17, 0xe000
	s_nop 0
	global_load_lds_dwordx4 v138, s[26:27]
	s_waitcnt vmcnt(8)
	s_waitcnt lgkmcnt(0)
	s_barrier
	s_setprio 1
	s_waitcnt lgkmcnt(0)
	v_mfma_f32_16x16x32_bf16 v[124:127], v[144:147], v[216:219], v[124:127]
	v_mfma_f32_16x16x32_bf16 v[120:123], v[152:155], v[216:219], v[120:123]
	v_mfma_f32_16x16x32_bf16 v[108:111], v[144:147], v[224:227], v[108:111]
	v_mfma_f32_16x16x32_bf16 v[104:107], v[152:155], v[224:227], v[104:107]
	v_mfma_f32_16x16x32_bf16 v[92:95], v[144:147], v[232:235], v[92:95]
	v_mfma_f32_16x16x32_bf16 v[88:91], v[152:155], v[232:235], v[88:91]
	v_mfma_f32_16x16x32_bf16 v[76:79], v[144:147], v[240:243], v[76:79]
	v_mfma_f32_16x16x32_bf16 v[72:75], v[152:155], v[240:243], v[72:75]
	v_mfma_f32_16x16x32_bf16 v[124:127], v[148:151], v[220:223], v[124:127]
	v_mfma_f32_16x16x32_bf16 v[120:123], v[156:159], v[220:223], v[120:123]
	v_mfma_f32_16x16x32_bf16 v[108:111], v[148:151], v[228:231], v[108:111]
	v_mfma_f32_16x16x32_bf16 v[104:107], v[156:159], v[228:231], v[104:107]
	v_mfma_f32_16x16x32_bf16 v[92:95], v[148:151], v[236:239], v[92:95]
	v_mfma_f32_16x16x32_bf16 v[88:91], v[156:159], v[236:239], v[88:91]
	v_mfma_f32_16x16x32_bf16 v[76:79], v[148:151], v[244:247], v[76:79]
	v_mfma_f32_16x16x32_bf16 v[72:75], v[156:159], v[244:247], v[72:75]
	s_setprio 0
	s_setprio 1
	v_mfma_f32_16x16x32_bf16 v[116:119], v[160:163], v[216:219], v[116:119]
	v_mfma_f32_16x16x32_bf16 v[112:115], v[168:171], v[216:219], v[112:115]
	v_mfma_f32_16x16x32_bf16 v[100:103], v[160:163], v[224:227], v[100:103]
	v_mfma_f32_16x16x32_bf16 v[96:99], v[168:171], v[224:227], v[96:99]
	v_mfma_f32_16x16x32_bf16 v[84:87], v[160:163], v[232:235], v[84:87]
	v_mfma_f32_16x16x32_bf16 v[80:83], v[168:171], v[232:235], v[80:83]
	v_mfma_f32_16x16x32_bf16 v[68:71], v[160:163], v[240:243], v[68:71]
	v_mfma_f32_16x16x32_bf16 v[64:67], v[168:171], v[240:243], v[64:67]
	v_mfma_f32_16x16x32_bf16 v[116:119], v[164:167], v[220:223], v[116:119]
	v_mfma_f32_16x16x32_bf16 v[112:115], v[172:175], v[220:223], v[112:115]
	v_mfma_f32_16x16x32_bf16 v[100:103], v[164:167], v[228:231], v[100:103]
	v_mfma_f32_16x16x32_bf16 v[96:99], v[172:175], v[228:231], v[96:99]
	v_mfma_f32_16x16x32_bf16 v[84:87], v[164:167], v[236:239], v[84:87]
	v_mfma_f32_16x16x32_bf16 v[80:83], v[172:175], v[236:239], v[80:83]
	v_mfma_f32_16x16x32_bf16 v[68:71], v[164:167], v[244:247], v[68:71]
	v_mfma_f32_16x16x32_bf16 v[64:67], v[172:175], v[244:247], v[64:67]
	s_setprio 0
	s_barrier
	s_add_i32 s26, s45, s16
	s_mov_b32 m0, s26
	ds_read_b128 v[216:219], v204 offset:16384
	ds_read_b128 v[220:223], v204 offset:17408
	ds_read_b128 v[224:227], v204 offset:18432
	ds_read_b128 v[228:231], v204 offset:19456
	ds_read_b128 v[232:235], v204 offset:20480
	ds_read_b128 v[236:239], v204 offset:21504
	ds_read_b128 v[240:243], v204 offset:22528
	ds_read_b128 v[244:247], v204 offset:23552
	global_load_lds_dwordx4 v130, s[36:37]
	s_add_i32 m0, s26, 0x2000
	s_add_u32 s26, s36, 0xb0000
	s_addc_u32 s27, s37, 0
	s_add_i32 s52, s46, s16
	global_load_lds_dwordx4 v134, s[36:37]
	s_mov_b32 m0, s52
	s_nop 0
	global_load_lds_dwordx4 v130, s[26:27]
	s_add_i32 m0, s52, 0x2000
	s_nop 0
	global_load_lds_dwordx4 v134, s[26:27]
	s_mov_b32 m0, s17
	s_nop 0
	global_load_lds_dwordx4 v128, s[38:39]
	s_mov_b32 m0, s28
	s_nop 0
	global_load_lds_dwordx4 v132, s[38:39]
	s_waitcnt vmcnt(8)
	s_waitcnt lgkmcnt(0)
	s_barrier
	s_setprio 1
	s_waitcnt lgkmcnt(0)
	v_mfma_f32_16x16x32_bf16 v[60:63], v[144:147], v[216:219], v[60:63]
	v_mfma_f32_16x16x32_bf16 v[56:59], v[152:155], v[216:219], v[56:59]
	v_mfma_f32_16x16x32_bf16 v[44:47], v[144:147], v[224:227], v[44:47]
	v_mfma_f32_16x16x32_bf16 v[40:43], v[152:155], v[224:227], v[40:43]
	v_mfma_f32_16x16x32_bf16 v[28:31], v[144:147], v[232:235], v[28:31]
	v_mfma_f32_16x16x32_bf16 v[24:27], v[152:155], v[232:235], v[24:27]
	v_mfma_f32_16x16x32_bf16 v[12:15], v[144:147], v[240:243], v[12:15]
	v_mfma_f32_16x16x32_bf16 v[8:11], v[152:155], v[240:243], v[8:11]
	v_mfma_f32_16x16x32_bf16 v[60:63], v[148:151], v[220:223], v[60:63]
	v_mfma_f32_16x16x32_bf16 v[56:59], v[156:159], v[220:223], v[56:59]
	v_mfma_f32_16x16x32_bf16 v[44:47], v[148:151], v[228:231], v[44:47]
	v_mfma_f32_16x16x32_bf16 v[40:43], v[156:159], v[228:231], v[40:43]
	v_mfma_f32_16x16x32_bf16 v[28:31], v[148:151], v[236:239], v[28:31]
	v_mfma_f32_16x16x32_bf16 v[24:27], v[156:159], v[236:239], v[24:27]
	v_mfma_f32_16x16x32_bf16 v[12:15], v[148:151], v[244:247], v[12:15]
	v_mfma_f32_16x16x32_bf16 v[8:11], v[156:159], v[244:247], v[8:11]
	s_setprio 0
	s_setprio 1
	v_mfma_f32_16x16x32_bf16 v[52:55], v[160:163], v[216:219], v[52:55]
	v_mfma_f32_16x16x32_bf16 v[48:51], v[168:171], v[216:219], v[48:51]
	v_mfma_f32_16x16x32_bf16 v[36:39], v[160:163], v[224:227], v[36:39]
	v_mfma_f32_16x16x32_bf16 v[32:35], v[168:171], v[224:227], v[32:35]
	v_mfma_f32_16x16x32_bf16 v[20:23], v[160:163], v[232:235], v[20:23]
	v_mfma_f32_16x16x32_bf16 v[16:19], v[168:171], v[232:235], v[16:19]
	v_mfma_f32_16x16x32_bf16 v[4:7], v[160:163], v[240:243], v[4:7]
	v_mfma_f32_16x16x32_bf16 v[0:3], v[168:171], v[240:243], v[0:3]
	v_mfma_f32_16x16x32_bf16 v[52:55], v[164:167], v[220:223], v[52:55]
	v_mfma_f32_16x16x32_bf16 v[48:51], v[172:175], v[220:223], v[48:51]
	v_mfma_f32_16x16x32_bf16 v[36:39], v[164:167], v[228:231], v[36:39]
	v_mfma_f32_16x16x32_bf16 v[32:35], v[172:175], v[228:231], v[32:35]
	v_mfma_f32_16x16x32_bf16 v[20:23], v[164:167], v[236:239], v[20:23]
	v_mfma_f32_16x16x32_bf16 v[16:19], v[172:175], v[236:239], v[16:19]
	v_mfma_f32_16x16x32_bf16 v[4:7], v[164:167], v[244:247], v[4:7]
	v_mfma_f32_16x16x32_bf16 v[0:3], v[172:175], v[244:247], v[0:3]
	s_setprio 0
	s_barrier
; #define PG8_STAGE(bufoff, gbase, voff) do { _Pragma("unroll") for (int _i = 0; _i < 2; ++_i) \
;         __builtin_amdgcn_global_load_lds((const unsigned*)((const char*)(gbase) + (voff)[_i]), (LAS unsigned*)(lds + (bufoff) + ldsw + _i * 8192), 16, 0, 0); } while (0)
; #define PG8_LDA(dst, b, h) do { _Pragma("unroll") for (int m = 0; m < 4; ++m) _Pragma("unroll") for (int k = 0; k < 2; ++k) dst[m][k] = *(const LAS bf16x8*)(lds + PG8_SA(b, h) + aoff + m * 2048 + k * 1024); } while (0)
; #define PG8_LDB(dst, b, h) do { _Pragma("unroll") for (int n = 0; n < 2; ++n) _Pragma("unroll") for (int k = 0; k < 2; ++k) dst[n][k] = *(const LAS bf16x8*)(lds + PG8_SB(b, h) + boff + n * 2048 + k * 1024); } while (0)
; #define PG8_MMA(ai, bj, At, Bt) do { __builtin_amdgcn_s_setprio(1); _Pragma("unroll") for (int m = 0; m < 4; ++m) _Pragma("unroll") for (int n = 0; n < 2; ++n) _Pragma("unroll") for (int k = 0; k < 2; ++k) \
;         acc[ai][bj][m][n] = __builtin_amdgcn_mfma_f32_16x16x32_bf16(Bt[n][k], At[m][k], acc[ai][bj][m][n], 0, 0, 0); __builtin_amdgcn_s_setprio(0); } while (0)
; #define PG8_WAIT_V(n) asm volatile("s_waitcnt vmcnt(" #n ")" ::: "memory")
; #define PG8_WAIT_L(n) asm volatile("s_waitcnt lgkmcnt(" #n ")" ::: "memory")
; #define PG8_BAR __builtin_amdgcn_s_barrier()
; #define PG8_SCHED __builtin_amdgcn_sched_barrier(0)
; template <class Epi>
; __device__ __forceinline__ void gemm_phase(LAS unsigned char* lds, const Gemm g, const StaticOrder& S, const Epi& E) {
;     ...
;             PG8_LDB(B0, 1, 0); PG8_LDB(B1, 1, 1); PG8_SCHED; PG8_LDA(At, 1, 0); PG8_STAGE(PG8_SA(0, 1), a2 + hsA, voffA);
;             PG8_WAIT_V(8); PG8_WAIT_L(0); PG8_BAR; PG8_MMA(0, 0, At, B0); PG8_MMA(0, 1, At, B1); PG8_BAR; PG8_SCHED;
;             PG8_LDA(At, 1, 1); PG8_STAGE(PG8_SB(1, 0), b3, voffB); PG8_STAGE(PG8_SB(1, 1), b3 + hsB, voffB); PG8_STAGE(PG8_SA(1, 0), a3, voffA);
;             PG8_WAIT_V(8); PG8_WAIT_L(0); PG8_BAR; PG8_MMA(1, 0, At, B0); PG8_MMA(1, 1, At, B1); PG8_BAR; PG8_SCHED;
;         }
	s_add_i32 s52, 0, 0x18000
	s_add_i32 s53, 0, 0x1c000
	v_add_u32_e32 v156, s52, v184
	v_add_u32_e32 v172, s53, v184
	ds_read_b128 v[144:147], v156
	ds_read_b128 v[148:151], v156 offset:1024
	ds_read_b128 v[152:155], v156 offset:2048
	ds_read_b128 v[156:159], v156 offset:3072
	ds_read_b128 v[160:163], v172
	ds_read_b128 v[164:167], v172 offset:1024
	ds_read_b128 v[168:171], v172 offset:2048
	ds_read_b128 v[172:175], v172 offset:3072
	s_add_u32 s26, s38, 0xb0000
	s_addc_u32 s27, s39, 0
	s_mov_b32 m0, s29
	ds_read_b128 v[216:219], v204 offset:32768
	ds_read_b128 v[220:223], v204 offset:33792
	ds_read_b128 v[224:227], v204 offset:34816
	ds_read_b128 v[228:231], v204 offset:35840
	ds_read_b128 v[232:235], v204 offset:36864
	ds_read_b128 v[236:239], v204 offset:37888
	ds_read_b128 v[240:243], v204 offset:38912
	ds_read_b128 v[244:247], v204 offset:39936
	global_load_lds_dwordx4 v128, s[26:27]
	s_mov_b32 m0, s30
	s_nop 0
	global_load_lds_dwordx4 v132, s[26:27]
	s_waitcnt vmcnt(8)
	s_waitcnt lgkmcnt(0)
	s_barrier
	s_setprio 1
	s_waitcnt lgkmcnt(0)
	v_mfma_f32_16x16x32_bf16 v[124:127], v[144:147], v[216:219], v[124:127]
	v_mfma_f32_16x16x32_bf16 v[120:123], v[152:155], v[216:219], v[120:123]
	v_mfma_f32_16x16x32_bf16 v[108:111], v[144:147], v[224:227], v[108:111]
	v_mfma_f32_16x16x32_bf16 v[104:107], v[152:155], v[224:227], v[104:107]
	v_mfma_f32_16x16x32_bf16 v[92:95], v[144:147], v[232:235], v[92:95]
	v_mfma_f32_16x16x32_bf16 v[88:91], v[152:155], v[232:235], v[88:91]
	v_mfma_f32_16x16x32_bf16 v[76:79], v[144:147], v[240:243], v[76:79]
	v_mfma_f32_16x16x32_bf16 v[72:75], v[152:155], v[240:243], v[72:75]
	v_mfma_f32_16x16x32_bf16 v[124:127], v[148:151], v[220:223], v[124:127]
	v_mfma_f32_16x16x32_bf16 v[120:123], v[156:159], v[220:223], v[120:123]
	v_mfma_f32_16x16x32_bf16 v[108:111], v[148:151], v[228:231], v[108:111]
	v_mfma_f32_16x16x32_bf16 v[104:107], v[156:159], v[228:231], v[104:107]
	v_mfma_f32_16x16x32_bf16 v[92:95], v[148:151], v[236:239], v[92:95]
	v_mfma_f32_16x16x32_bf16 v[88:91], v[156:159], v[236:239], v[88:91]
	v_mfma_f32_16x16x32_bf16 v[76:79], v[148:151], v[244:247], v[76:79]
	v_mfma_f32_16x16x32_bf16 v[72:75], v[156:159], v[244:247], v[72:75]
	s_setprio 0
	s_setprio 1
	v_mfma_f32_16x16x32_bf16 v[116:119], v[160:163], v[216:219], v[116:119]
	v_mfma_f32_16x16x32_bf16 v[112:115], v[168:171], v[216:219], v[112:115]
	v_mfma_f32_16x16x32_bf16 v[100:103], v[160:163], v[224:227], v[100:103]
	v_mfma_f32_16x16x32_bf16 v[96:99], v[168:171], v[224:227], v[96:99]
	v_mfma_f32_16x16x32_bf16 v[84:87], v[160:163], v[232:235], v[84:87]
	v_mfma_f32_16x16x32_bf16 v[80:83], v[168:171], v[232:235], v[80:83]
	v_mfma_f32_16x16x32_bf16 v[68:71], v[160:163], v[240:243], v[68:71]
	v_mfma_f32_16x16x32_bf16 v[64:67], v[168:171], v[240:243], v[64:67]
	v_mfma_f32_16x16x32_bf16 v[116:119], v[164:167], v[220:223], v[116:119]
	v_mfma_f32_16x16x32_bf16 v[112:115], v[172:175], v[220:223], v[112:115]
	v_mfma_f32_16x16x32_bf16 v[100:103], v[164:167], v[228:231], v[100:103]
	v_mfma_f32_16x16x32_bf16 v[96:99], v[172:175], v[228:231], v[96:99]
	v_mfma_f32_16x16x32_bf16 v[84:87], v[164:167], v[236:239], v[84:87]
	v_mfma_f32_16x16x32_bf16 v[80:83], v[172:175], v[236:239], v[80:83]
	v_mfma_f32_16x16x32_bf16 v[68:71], v[164:167], v[244:247], v[68:71]
	v_mfma_f32_16x16x32_bf16 v[64:67], v[172:175], v[244:247], v[64:67]
	s_setprio 0
	s_barrier
	s_add_u32 s98, s36, 0x80
	s_addc_u32 s99, s37, 0
	s_add_u32 s100, s38, 0x80
	s_addc_u32 s101, s39, 0
	s_add_i32 s26, s52, s16
	s_mov_b32 m0, s26
	ds_read_b128 v[216:219], v204 offset:49152
	ds_read_b128 v[220:223], v204 offset:50176
	ds_read_b128 v[224:227], v204 offset:51200
	ds_read_b128 v[228:231], v204 offset:52224
	ds_read_b128 v[232:235], v204 offset:53248
	ds_read_b128 v[236:239], v204 offset:54272
	ds_read_b128 v[240:243], v204 offset:55296
	ds_read_b128 v[244:247], v204 offset:56320
	global_load_lds_dwordx4 v130, s[98:99]
	s_add_i32 m0, s26, 0x2000
	s_add_u32 s26, s36, 0xb0080
	s_addc_u32 s27, s37, 0
	s_add_i32 s36, s53, s16
	global_load_lds_dwordx4 v134, s[98:99]
	s_mov_b32 m0, s36
	s_nop 0
	global_load_lds_dwordx4 v130, s[26:27]
	s_add_i32 m0, s36, 0x2000
	s_nop 0
	global_load_lds_dwordx4 v134, s[26:27]
	s_mov_b32 m0, s41
	s_nop 0
	global_load_lds_dwordx4 v128, s[100:101]
	s_mov_b32 m0, s42
	s_nop 0
	global_load_lds_dwordx4 v132, s[100:101]
	s_waitcnt vmcnt(8)
	s_waitcnt lgkmcnt(0)
	s_barrier
	s_setprio 1
	s_waitcnt lgkmcnt(0)
	v_mfma_f32_16x16x32_bf16 v[60:63], v[144:147], v[216:219], v[60:63]
	v_mfma_f32_16x16x32_bf16 v[56:59], v[152:155], v[216:219], v[56:59]
	v_mfma_f32_16x16x32_bf16 v[44:47], v[144:147], v[224:227], v[44:47]
	v_mfma_f32_16x16x32_bf16 v[40:43], v[152:155], v[224:227], v[40:43]
	v_mfma_f32_16x16x32_bf16 v[28:31], v[144:147], v[232:235], v[28:31]
	v_mfma_f32_16x16x32_bf16 v[24:27], v[152:155], v[232:235], v[24:27]
	v_mfma_f32_16x16x32_bf16 v[12:15], v[144:147], v[240:243], v[12:15]
	v_mfma_f32_16x16x32_bf16 v[8:11], v[152:155], v[240:243], v[8:11]
	v_mfma_f32_16x16x32_bf16 v[60:63], v[148:151], v[220:223], v[60:63]
	v_mfma_f32_16x16x32_bf16 v[56:59], v[156:159], v[220:223], v[56:59]
	v_mfma_f32_16x16x32_bf16 v[44:47], v[148:151], v[228:231], v[44:47]
	v_mfma_f32_16x16x32_bf16 v[40:43], v[156:159], v[228:231], v[40:43]
	v_mfma_f32_16x16x32_bf16 v[28:31], v[148:151], v[236:239], v[28:31]
	v_mfma_f32_16x16x32_bf16 v[24:27], v[156:159], v[236:239], v[24:27]
	v_mfma_f32_16x16x32_bf16 v[12:15], v[148:151], v[244:247], v[12:15]
	v_mfma_f32_16x16x32_bf16 v[8:11], v[156:159], v[244:247], v[8:11]
	s_setprio 0
	s_setprio 1
	v_mfma_f32_16x16x32_bf16 v[52:55], v[160:163], v[216:219], v[52:55]
	v_mfma_f32_16x16x32_bf16 v[48:51], v[168:171], v[216:219], v[48:51]
	v_mfma_f32_16x16x32_bf16 v[36:39], v[160:163], v[224:227], v[36:39]
	v_mfma_f32_16x16x32_bf16 v[32:35], v[168:171], v[224:227], v[32:35]
	v_mfma_f32_16x16x32_bf16 v[20:23], v[160:163], v[232:235], v[20:23]
	v_mfma_f32_16x16x32_bf16 v[16:19], v[168:171], v[232:235], v[16:19]
	v_mfma_f32_16x16x32_bf16 v[4:7], v[160:163], v[240:243], v[4:7]
	v_mfma_f32_16x16x32_bf16 v[0:3], v[168:171], v[240:243], v[0:3]
	v_mfma_f32_16x16x32_bf16 v[52:55], v[164:167], v[220:223], v[52:55]
	v_mfma_f32_16x16x32_bf16 v[48:51], v[172:175], v[220:223], v[48:51]
	v_mfma_f32_16x16x32_bf16 v[36:39], v[164:167], v[228:231], v[36:39]
	v_mfma_f32_16x16x32_bf16 v[32:35], v[172:175], v[228:231], v[32:35]
	v_mfma_f32_16x16x32_bf16 v[20:23], v[164:167], v[236:239], v[20:23]
	v_mfma_f32_16x16x32_bf16 v[16:19], v[172:175], v[236:239], v[16:19]
	v_mfma_f32_16x16x32_bf16 v[4:7], v[164:167], v[244:247], v[4:7]
	v_mfma_f32_16x16x32_bf16 v[0:3], v[172:175], v[244:247], v[0:3]
	s_setprio 0
	s_barrier
	s_add_i32 s51, s51, 2
	s_add_u32 s25, s25, 0x100
	s_addc_u32 s50, s50, 0
	s_cmp_gt_u32 s51, 41
	s_mov_b64 s[26:27], s[34:35]
	s_cbranch_scc0 .LBB0_1433
	s_and_b64 vcc, exec, s[18:19]
	s_cbranch_vccz .LBB0_1436
	s_barrier
